# speedup vs baseline: 1.0954x; 1.0638x over previous
.Lgo_entry:
	v_readlane_b32 s0, v236, 0
	s_cmpk_lg_u32 s0, 0x200
	s_cbranch_scc0 .Lgo_go
	s_branch .LBB0_65
.Lgo_go:
	v_lshrrev_b32_e32 v90, 3, v93
	v_and_b32_e32 v195, 7, v93
	v_bfe_u32 v232, v90, 1, 3
	v_xor_b32_e32 v195, v195, v232
	v_lshlrev_b32_e32 v195, 4, v195
	v_lshl_or_b32 v166, v90, 12, v195
	v_add_u32_e32 v167, 0x20000, v166
	v_add_u32_e32 v168, 0x40000, v166
	v_add_u32_e32 v169, 0x60000, v166
	v_and_b32_e32 v232, 12, v90
	v_lshlrev_b32_e32 v232, 1, v232
	v_and_or_b32 v232, v90, 3, v232
	v_lshrrev_b32_e32 v90, 4, v90
	v_lshl_or_b32 v232, v90, 2, v232
	v_lshl_or_b32 v170, v232, 12, v195
	v_add_u32_e32 v171, 0x20000, v170
	v_add_u32_e32 v172, 0x40000, v170
	v_add_u32_e32 v173, 0x60000, v170
	v_lshrrev_b32_e32 v90, 6, v93
	v_and_b32_e32 v195, 15, v93
	v_readfirstlane_b32 s17, v90
	v_bfe_u32 v232, v93, 4, 2
	s_lshl_b32 s14, s17, 10
	s_lshr_b32 s20, s17, 1
	s_and_b32 s21, s17, 1
	s_lshl_b32 s20, s20, 6
	s_lshl_b32 s21, s21, 6
	v_bfe_u32 v90, v195, 1, 3
	v_xor_b32_e32 v90, v90, v232
	v_lshlrev_b32_e32 v90, 4, v90
	v_add_u32_e32 v229, s20, v195
	v_add_u32_e32 v231, s21, v195
	v_lshl_or_b32 v228, v229, 7, v90
	v_lshl_or_b32 v230, v231, 7, v90
	v_xor_b32_e32 v229, 64, v228
	v_xor_b32_e32 v231, 64, v230
	v_lshrrev_b32_e32 v232, 7, v228
	v_bfe_u32 v195, v93, 4, 2
	v_lshrrev_b32_e32 v90, 6, v93
	v_and_b32_e32 v90, 1, v90
	v_lshlrev_b32_e32 v90, 6, v90
	v_lshl_add_u32 v195, v195, 3, v90
	v_lshlrev_b32_e32 v90, 2, v195
	v_lshl_add_u32 v89, v232, 13, v90
	s_and_b32 s0, s2, 7
	s_lshl_b32 s0, s0, 3
	s_bfe_u32 s1, s2, 0x30003
	s_or_b32 s23, s0, s1
	s_lshr_b32 s18, s2, 6
	s_add_u32 s19, s18, 8
	v_readlane_b32 s4, v236, 51
	v_readlane_b32 s5, v236, 52
	s_lshl_b32 s0, s23, 19
	s_add_u32 s4, s4, s0
	s_addc_u32 s5, s5, 0
	v_readlane_b32 s10, v233, 24
	v_readlane_b32 s6, v236, 57
	v_readlane_b32 s7, v236, 58
	v_readlane_b32 s11, v236, 59
	v_readlane_b32 s12, v236, 60
	s_bitcmp1_b32 s10, 0
	s_cselect_b32 s6, s11, s6
	s_cselect_b32 s7, s12, s7
	s_lshl_b32 s0, s18, 19
	s_add_u32 s6, s6, s0
	s_addc_u32 s7, s7, 0
	s_add_u32 s8, s6, 0x400000
	s_addc_u32 s9, s7, 0
	s_movk_i32 s16, 4
	s_cmpk_lt_u32 s2, 0x100
	s_addc_u32 s16, s16, 0
	s_add_i32 m0, s14, 0x0
	s_nop 0
	global_load_lds_dwordx4 v166, s[4:5]
	s_add_i32 m0, s14, 0x1000
	s_nop 0
	global_load_lds_dwordx4 v167, s[4:5]
	s_add_i32 m0, s14, 0x2000
	s_nop 0
	global_load_lds_dwordx4 v168, s[4:5]
	s_add_i32 m0, s14, 0x3000
	s_nop 0
	global_load_lds_dwordx4 v169, s[4:5]
	s_add_i32 m0, s14, 0x4000
	s_nop 0
	global_load_lds_dwordx4 v170, s[8:9]
	s_add_i32 m0, s14, 0x5000
	s_nop 0
	global_load_lds_dwordx4 v171, s[8:9]
	s_add_i32 m0, s14, 0x6000
	s_nop 0
	global_load_lds_dwordx4 v172, s[8:9]
	s_add_i32 m0, s14, 0x7000
	s_nop 0
	global_load_lds_dwordx4 v173, s[8:9]
	s_add_i32 m0, s14, 0x8000
	s_nop 0
	global_load_lds_dwordx4 v170, s[6:7]
	s_add_i32 m0, s14, 0x9000
	s_nop 0
	global_load_lds_dwordx4 v171, s[6:7]
	s_add_i32 m0, s14, 0xa000
	s_nop 0
	global_load_lds_dwordx4 v172, s[6:7]
	s_add_i32 m0, s14, 0xb000
	s_nop 0
	global_load_lds_dwordx4 v173, s[6:7]
	v_add_u32_e32 v166, 0x80, v166
	v_add_u32_e32 v167, 0x80, v167
	v_add_u32_e32 v168, 0x80, v168
	v_add_u32_e32 v169, 0x80, v169
	v_add_u32_e32 v170, 0x80, v170
	v_add_u32_e32 v171, 0x80, v171
	v_add_u32_e32 v172, 0x80, v172
	v_add_u32_e32 v173, 0x80, v173

.Lgo_k_o:
	s_waitcnt vmcnt(0)
	s_barrier
	s_add_i32 m0, s14, 0xc000
	s_nop 0
	global_load_lds_dwordx4 v170, s[6:7]
	s_add_i32 m0, s14, 0xd000
	s_nop 0
	global_load_lds_dwordx4 v171, s[6:7]
	s_add_i32 m0, s14, 0xe000
	s_nop 0
	global_load_lds_dwordx4 v172, s[6:7]
	s_add_i32 m0, s14, 0xf000
	s_nop 0
	global_load_lds_dwordx4 v173, s[6:7]
	ds_read_b128 v[196:199], v228 offset:0
	ds_read_b128 v[200:203], v228 offset:2048
	ds_read_b128 v[204:207], v228 offset:4096
	ds_read_b128 v[208:211], v228 offset:6144
	ds_read_b128 v[212:215], v229 offset:0
	ds_read_b128 v[216:219], v229 offset:2048
	ds_read_b128 v[220:223], v229 offset:4096
	ds_read_b128 v[224:227], v229 offset:6144
	ds_read_b128 v[64:67], v230 offset:16384
	ds_read_b128 v[68:71], v230 offset:18432
	ds_read_b128 v[72:75], v230 offset:20480
	ds_read_b128 v[76:79], v230 offset:22528
	ds_read_b128 v[80:83], v231 offset:16384
	ds_read_b128 v[84:87], v231 offset:18432
	ds_read_b128 v[158:161], v231 offset:20480
	ds_read_b128 v[162:165], v231 offset:22528
	s_waitcnt lgkmcnt(0)
	s_barrier
	s_setprio 1
	s_add_i32 m0, s14, 0x0
	v_mfma_f32_16x16x32_bf16 v[94:97], v[64:67], v[196:199], v[94:97]
	global_load_lds_dwordx4 v166, s[4:5]
	v_mfma_f32_16x16x32_bf16 v[110:113], v[64:67], v[200:203], v[110:113]
	s_add_i32 m0, s14, 0x1000
	v_mfma_f32_16x16x32_bf16 v[126:129], v[64:67], v[204:207], v[126:129]
	global_load_lds_dwordx4 v167, s[4:5]
	v_mfma_f32_16x16x32_bf16 v[142:145], v[64:67], v[208:211], v[142:145]
	ds_read_b128 v[64:67], v230 offset:32768
	s_add_i32 m0, s14, 0x2000
	v_mfma_f32_16x16x32_bf16 v[98:101], v[68:71], v[196:199], v[98:101]
	global_load_lds_dwordx4 v168, s[4:5]
	v_mfma_f32_16x16x32_bf16 v[114:117], v[68:71], v[200:203], v[114:117]
	s_add_i32 m0, s14, 0x3000
	v_mfma_f32_16x16x32_bf16 v[130:133], v[68:71], v[204:207], v[130:133]
	global_load_lds_dwordx4 v169, s[4:5]
	v_mfma_f32_16x16x32_bf16 v[146:149], v[68:71], v[208:211], v[146:149]
	ds_read_b128 v[68:71], v230 offset:34816
	s_add_i32 m0, s14, 0x4000
	v_mfma_f32_16x16x32_bf16 v[102:105], v[72:75], v[196:199], v[102:105]
	global_load_lds_dwordx4 v170, s[8:9]
	v_mfma_f32_16x16x32_bf16 v[118:121], v[72:75], v[200:203], v[118:121]
	s_add_i32 m0, s14, 0x5000
	v_mfma_f32_16x16x32_bf16 v[134:137], v[72:75], v[204:207], v[134:137]
	global_load_lds_dwordx4 v171, s[8:9]
	v_mfma_f32_16x16x32_bf16 v[150:153], v[72:75], v[208:211], v[150:153]
	ds_read_b128 v[72:75], v230 offset:36864
	s_add_i32 m0, s14, 0x6000
	v_mfma_f32_16x16x32_bf16 v[106:109], v[76:79], v[196:199], v[106:109]
	global_load_lds_dwordx4 v172, s[8:9]
	v_mfma_f32_16x16x32_bf16 v[122:125], v[76:79], v[200:203], v[122:125]
	s_add_i32 m0, s14, 0x7000
	v_mfma_f32_16x16x32_bf16 v[138:141], v[76:79], v[204:207], v[138:141]
	global_load_lds_dwordx4 v173, s[8:9]
	v_mfma_f32_16x16x32_bf16 v[154:157], v[76:79], v[208:211], v[154:157]
	ds_read_b128 v[76:79], v230 offset:38912
	v_mfma_f32_16x16x32_bf16 v[94:97], v[80:83], v[212:215], v[94:97]
	v_add_u32_e32 v166, 0x80, v166
	v_mfma_f32_16x16x32_bf16 v[110:113], v[80:83], v[216:219], v[110:113]
	v_add_u32_e32 v167, 0x80, v167
	v_mfma_f32_16x16x32_bf16 v[126:129], v[80:83], v[220:223], v[126:129]
	v_add_u32_e32 v168, 0x80, v168
	v_mfma_f32_16x16x32_bf16 v[142:145], v[80:83], v[224:227], v[142:145]
	v_add_u32_e32 v169, 0x80, v169
	ds_read_b128 v[80:83], v231 offset:32768
	v_mfma_f32_16x16x32_bf16 v[98:101], v[84:87], v[212:215], v[98:101]
	v_add_u32_e32 v170, 0x80, v170
	v_mfma_f32_16x16x32_bf16 v[114:117], v[84:87], v[216:219], v[114:117]
	v_add_u32_e32 v171, 0x80, v171
	v_mfma_f32_16x16x32_bf16 v[130:133], v[84:87], v[220:223], v[130:133]
	v_add_u32_e32 v172, 0x80, v172
	v_mfma_f32_16x16x32_bf16 v[146:149], v[84:87], v[224:227], v[146:149]
	v_add_u32_e32 v173, 0x80, v173
	ds_read_b128 v[84:87], v231 offset:34816
	v_mfma_f32_16x16x32_bf16 v[102:105], v[158:161], v[212:215], v[102:105]
	v_mfma_f32_16x16x32_bf16 v[118:121], v[158:161], v[216:219], v[118:121]
	v_mfma_f32_16x16x32_bf16 v[134:137], v[158:161], v[220:223], v[134:137]
	v_mfma_f32_16x16x32_bf16 v[150:153], v[158:161], v[224:227], v[150:153]
	ds_read_b128 v[158:161], v231 offset:36864
	v_mfma_f32_16x16x32_bf16 v[106:109], v[162:165], v[212:215], v[106:109]
	v_mfma_f32_16x16x32_bf16 v[122:125], v[162:165], v[216:219], v[122:125]
	v_mfma_f32_16x16x32_bf16 v[138:141], v[162:165], v[220:223], v[138:141]
	v_mfma_f32_16x16x32_bf16 v[154:157], v[162:165], v[224:227], v[154:157]
	ds_read_b128 v[162:165], v231 offset:38912
	s_waitcnt lgkmcnt(7)
	v_mfma_f32_16x16x32_bf16 v[0:3], v[64:67], v[196:199], v[0:3]
	v_mfma_f32_16x16x32_bf16 v[16:19], v[64:67], v[200:203], v[16:19]
	v_mfma_f32_16x16x32_bf16 v[32:35], v[64:67], v[204:207], v[32:35]
	v_mfma_f32_16x16x32_bf16 v[48:51], v[64:67], v[208:211], v[48:51]
	s_waitcnt lgkmcnt(6)
	v_mfma_f32_16x16x32_bf16 v[4:7], v[68:71], v[196:199], v[4:7]
	v_mfma_f32_16x16x32_bf16 v[20:23], v[68:71], v[200:203], v[20:23]
	v_mfma_f32_16x16x32_bf16 v[36:39], v[68:71], v[204:207], v[36:39]
	v_mfma_f32_16x16x32_bf16 v[52:55], v[68:71], v[208:211], v[52:55]
	s_waitcnt lgkmcnt(5)
	v_mfma_f32_16x16x32_bf16 v[8:11], v[72:75], v[196:199], v[8:11]
	v_mfma_f32_16x16x32_bf16 v[24:27], v[72:75], v[200:203], v[24:27]
	v_mfma_f32_16x16x32_bf16 v[40:43], v[72:75], v[204:207], v[40:43]
	v_mfma_f32_16x16x32_bf16 v[56:59], v[72:75], v[208:211], v[56:59]
	s_waitcnt lgkmcnt(4)
	v_mfma_f32_16x16x32_bf16 v[12:15], v[76:79], v[196:199], v[12:15]
	v_mfma_f32_16x16x32_bf16 v[28:31], v[76:79], v[200:203], v[28:31]
	v_mfma_f32_16x16x32_bf16 v[44:47], v[76:79], v[204:207], v[44:47]
	v_mfma_f32_16x16x32_bf16 v[60:63], v[76:79], v[208:211], v[60:63]
	s_waitcnt lgkmcnt(3)
	v_mfma_f32_16x16x32_bf16 v[0:3], v[80:83], v[212:215], v[0:3]
	v_mfma_f32_16x16x32_bf16 v[16:19], v[80:83], v[216:219], v[16:19]
	v_mfma_f32_16x16x32_bf16 v[32:35], v[80:83], v[220:223], v[32:35]
	v_mfma_f32_16x16x32_bf16 v[48:51], v[80:83], v[224:227], v[48:51]
	s_waitcnt lgkmcnt(2)
	v_mfma_f32_16x16x32_bf16 v[4:7], v[84:87], v[212:215], v[4:7]
	v_mfma_f32_16x16x32_bf16 v[20:23], v[84:87], v[216:219], v[20:23]
	v_mfma_f32_16x16x32_bf16 v[36:39], v[84:87], v[220:223], v[36:39]
	v_mfma_f32_16x16x32_bf16 v[52:55], v[84:87], v[224:227], v[52:55]
	s_waitcnt lgkmcnt(1)
	v_mfma_f32_16x16x32_bf16 v[8:11], v[158:161], v[212:215], v[8:11]
	v_mfma_f32_16x16x32_bf16 v[24:27], v[158:161], v[216:219], v[24:27]
	v_mfma_f32_16x16x32_bf16 v[40:43], v[158:161], v[220:223], v[40:43]
	v_mfma_f32_16x16x32_bf16 v[56:59], v[158:161], v[224:227], v[56:59]
	s_waitcnt lgkmcnt(0)
	v_mfma_f32_16x16x32_bf16 v[12:15], v[162:165], v[212:215], v[12:15]
	v_mfma_f32_16x16x32_bf16 v[28:31], v[162:165], v[216:219], v[28:31]
	v_mfma_f32_16x16x32_bf16 v[44:47], v[162:165], v[220:223], v[44:47]
	v_mfma_f32_16x16x32_bf16 v[60:63], v[162:165], v[224:227], v[60:63]
	s_setprio 0
	s_waitcnt vmcnt(0)
	s_barrier
	ds_read_b128 v[196:199], v228 offset:0
	ds_read_b128 v[200:203], v228 offset:2048
	ds_read_b128 v[204:207], v228 offset:4096
	ds_read_b128 v[208:211], v228 offset:6144
	ds_read_b128 v[212:215], v229 offset:0
	ds_read_b128 v[216:219], v229 offset:2048
	ds_read_b128 v[220:223], v229 offset:4096
	ds_read_b128 v[224:227], v229 offset:6144
	ds_read_b128 v[64:67], v230 offset:16384
	ds_read_b128 v[68:71], v230 offset:18432
	ds_read_b128 v[72:75], v230 offset:20480
	ds_read_b128 v[76:79], v230 offset:22528
	ds_read_b128 v[80:83], v231 offset:16384
	ds_read_b128 v[84:87], v231 offset:18432
	ds_read_b128 v[158:161], v231 offset:20480
	ds_read_b128 v[162:165], v231 offset:22528
	s_cmp_lg_u32 s15, 1
	s_cbranch_scc1 .Lhk_done_o
	s_add_u32 s4, s4, 0xfffff000
	s_addc_u32 s5, s5, -1
	s_add_u32 s6, s6, 0xfffff000
	s_addc_u32 s7, s7, -1
	s_add_u32 s8, s8, 0xfffff000
	s_addc_u32 s9, s9, -1
	s_cmp_eq_u32 s16, 1
	s_cbranch_scc1 .Lhk_done_o
	s_cmp_eq_u32 s16, 2
	s_cbranch_scc0 .Lhk_reg_o
	s_cmpk_lt_u32 s2, 0x100
	s_cbranch_scc0 .Lhk_reg_o
	v_readlane_b32 s0, v236, 51
	v_readlane_b32 s1, v236, 52
	s_and_b32 s10, s2, 31
	s_add_u32 s10, s10, 256
	s_lshl_b32 s10, s10, 19
	s_add_u32 s4, s0, s10
	s_addc_u32 s5, s1, 0
	s_sub_u32 s4, s4, 0x4000
	s_subb_u32 s5, s5, 0
	v_readlane_b32 s10, v233, 24
	v_readlane_b32 s0, v236, 57
	v_readlane_b32 s1, v236, 58
	v_readlane_b32 s11, v236, 59
	v_readlane_b32 s12, v236, 60
	s_bitcmp1_b32 s10, 0
	s_cselect_b32 s0, s11, s0
	s_cselect_b32 s1, s12, s1
	s_lshr_b32 s10, s2, 5
	s_lshl_b32 s10, s10, 19
	s_add_u32 s6, s0, s10
	s_addc_u32 s7, s1, 0
	s_sub_u32 s6, s6, 0x4000
	s_subb_u32 s7, s7, 0
	s_add_u32 s8, s6, 0x400000
	s_addc_u32 s9, s7, 0
	s_branch .Lhk_done_o
.Lhk_reg_o:
	s_add_u32 s4, s4, 0x2000000
	s_addc_u32 s5, s5, 0
.Lhk_done_o:
	s_waitcnt lgkmcnt(0)
	s_barrier
	s_setprio 1
	s_add_i32 m0, s14, 0x0
	v_mfma_f32_16x16x32_bf16 v[94:97], v[64:67], v[196:199], v[94:97]
	global_load_lds_dwordx4 v166, s[4:5]
	v_mfma_f32_16x16x32_bf16 v[110:113], v[64:67], v[200:203], v[110:113]
	s_add_i32 m0, s14, 0x1000
	v_mfma_f32_16x16x32_bf16 v[126:129], v[64:67], v[204:207], v[126:129]
	global_load_lds_dwordx4 v167, s[4:5]
	v_mfma_f32_16x16x32_bf16 v[142:145], v[64:67], v[208:211], v[142:145]
	ds_read_b128 v[64:67], v230 offset:49152
	s_add_i32 m0, s14, 0x2000
	v_mfma_f32_16x16x32_bf16 v[98:101], v[68:71], v[196:199], v[98:101]
	global_load_lds_dwordx4 v168, s[4:5]
	v_mfma_f32_16x16x32_bf16 v[114:117], v[68:71], v[200:203], v[114:117]
	s_add_i32 m0, s14, 0x3000
	v_mfma_f32_16x16x32_bf16 v[130:133], v[68:71], v[204:207], v[130:133]
	global_load_lds_dwordx4 v169, s[4:5]
	v_mfma_f32_16x16x32_bf16 v[146:149], v[68:71], v[208:211], v[146:149]
	ds_read_b128 v[68:71], v230 offset:51200
	s_add_i32 m0, s14, 0x4000
	v_mfma_f32_16x16x32_bf16 v[102:105], v[72:75], v[196:199], v[102:105]
	global_load_lds_dwordx4 v170, s[8:9]
	v_mfma_f32_16x16x32_bf16 v[118:121], v[72:75], v[200:203], v[118:121]
	s_add_i32 m0, s14, 0x5000
	v_mfma_f32_16x16x32_bf16 v[134:137], v[72:75], v[204:207], v[134:137]
	global_load_lds_dwordx4 v171, s[8:9]
	v_mfma_f32_16x16x32_bf16 v[150:153], v[72:75], v[208:211], v[150:153]
	ds_read_b128 v[72:75], v230 offset:53248
	s_add_i32 m0, s14, 0x6000
	v_mfma_f32_16x16x32_bf16 v[106:109], v[76:79], v[196:199], v[106:109]
	global_load_lds_dwordx4 v172, s[8:9]
	v_mfma_f32_16x16x32_bf16 v[122:125], v[76:79], v[200:203], v[122:125]
	s_add_i32 m0, s14, 0x7000
	v_mfma_f32_16x16x32_bf16 v[138:141], v[76:79], v[204:207], v[138:141]
	global_load_lds_dwordx4 v173, s[8:9]
	v_mfma_f32_16x16x32_bf16 v[154:157], v[76:79], v[208:211], v[154:157]
	ds_read_b128 v[76:79], v230 offset:55296
	s_add_i32 m0, s14, 0x8000
	v_mfma_f32_16x16x32_bf16 v[94:97], v[80:83], v[212:215], v[94:97]
	global_load_lds_dwordx4 v170, s[6:7]
	v_mfma_f32_16x16x32_bf16 v[110:113], v[80:83], v[216:219], v[110:113]
	s_add_i32 m0, s14, 0x9000
	v_mfma_f32_16x16x32_bf16 v[126:129], v[80:83], v[220:223], v[126:129]
	global_load_lds_dwordx4 v171, s[6:7]
	v_mfma_f32_16x16x32_bf16 v[142:145], v[80:83], v[224:227], v[142:145]
	ds_read_b128 v[80:83], v231 offset:49152
	s_add_i32 m0, s14, 0xa000
	v_mfma_f32_16x16x32_bf16 v[98:101], v[84:87], v[212:215], v[98:101]
	global_load_lds_dwordx4 v172, s[6:7]
	v_mfma_f32_16x16x32_bf16 v[114:117], v[84:87], v[216:219], v[114:117]
	s_add_i32 m0, s14, 0xb000
	v_mfma_f32_16x16x32_bf16 v[130:133], v[84:87], v[220:223], v[130:133]
	global_load_lds_dwordx4 v173, s[6:7]
	v_mfma_f32_16x16x32_bf16 v[146:149], v[84:87], v[224:227], v[146:149]
	ds_read_b128 v[84:87], v231 offset:51200
	v_mfma_f32_16x16x32_bf16 v[102:105], v[158:161], v[212:215], v[102:105]
	v_add_u32_e32 v166, 0x80, v166
	v_mfma_f32_16x16x32_bf16 v[118:121], v[158:161], v[216:219], v[118:121]
	v_add_u32_e32 v167, 0x80, v167
	v_mfma_f32_16x16x32_bf16 v[134:137], v[158:161], v[220:223], v[134:137]
	v_add_u32_e32 v168, 0x80, v168
	v_mfma_f32_16x16x32_bf16 v[150:153], v[158:161], v[224:227], v[150:153]
	v_add_u32_e32 v169, 0x80, v169
	ds_read_b128 v[158:161], v231 offset:53248
	v_mfma_f32_16x16x32_bf16 v[106:109], v[162:165], v[212:215], v[106:109]
	v_add_u32_e32 v170, 0x80, v170
	v_mfma_f32_16x16x32_bf16 v[122:125], v[162:165], v[216:219], v[122:125]
	v_add_u32_e32 v171, 0x80, v171
	v_mfma_f32_16x16x32_bf16 v[138:141], v[162:165], v[220:223], v[138:141]
	v_add_u32_e32 v172, 0x80, v172
	v_mfma_f32_16x16x32_bf16 v[154:157], v[162:165], v[224:227], v[154:157]
	v_add_u32_e32 v173, 0x80, v173
	ds_read_b128 v[162:165], v231 offset:55296
	s_waitcnt lgkmcnt(7)
	v_mfma_f32_16x16x32_bf16 v[0:3], v[64:67], v[196:199], v[0:3]
	v_mfma_f32_16x16x32_bf16 v[16:19], v[64:67], v[200:203], v[16:19]
	v_mfma_f32_16x16x32_bf16 v[32:35], v[64:67], v[204:207], v[32:35]
	v_mfma_f32_16x16x32_bf16 v[48:51], v[64:67], v[208:211], v[48:51]
	s_waitcnt lgkmcnt(6)
	v_mfma_f32_16x16x32_bf16 v[4:7], v[68:71], v[196:199], v[4:7]
	v_mfma_f32_16x16x32_bf16 v[20:23], v[68:71], v[200:203], v[20:23]
	v_mfma_f32_16x16x32_bf16 v[36:39], v[68:71], v[204:207], v[36:39]
	v_mfma_f32_16x16x32_bf16 v[52:55], v[68:71], v[208:211], v[52:55]
	s_waitcnt lgkmcnt(5)
	v_mfma_f32_16x16x32_bf16 v[8:11], v[72:75], v[196:199], v[8:11]
	v_mfma_f32_16x16x32_bf16 v[24:27], v[72:75], v[200:203], v[24:27]
	v_mfma_f32_16x16x32_bf16 v[40:43], v[72:75], v[204:207], v[40:43]
	v_mfma_f32_16x16x32_bf16 v[56:59], v[72:75], v[208:211], v[56:59]
	s_waitcnt lgkmcnt(4)
	v_mfma_f32_16x16x32_bf16 v[12:15], v[76:79], v[196:199], v[12:15]
	v_mfma_f32_16x16x32_bf16 v[28:31], v[76:79], v[200:203], v[28:31]
	v_mfma_f32_16x16x32_bf16 v[44:47], v[76:79], v[204:207], v[44:47]
	v_mfma_f32_16x16x32_bf16 v[60:63], v[76:79], v[208:211], v[60:63]
	s_waitcnt lgkmcnt(3)
	v_mfma_f32_16x16x32_bf16 v[0:3], v[80:83], v[212:215], v[0:3]
	v_mfma_f32_16x16x32_bf16 v[16:19], v[80:83], v[216:219], v[16:19]
	v_mfma_f32_16x16x32_bf16 v[32:35], v[80:83], v[220:223], v[32:35]
	v_mfma_f32_16x16x32_bf16 v[48:51], v[80:83], v[224:227], v[48:51]
	s_waitcnt lgkmcnt(2)
	v_mfma_f32_16x16x32_bf16 v[4:7], v[84:87], v[212:215], v[4:7]
	v_mfma_f32_16x16x32_bf16 v[20:23], v[84:87], v[216:219], v[20:23]
	v_mfma_f32_16x16x32_bf16 v[36:39], v[84:87], v[220:223], v[36:39]
	v_mfma_f32_16x16x32_bf16 v[52:55], v[84:87], v[224:227], v[52:55]
	s_waitcnt lgkmcnt(1)
	v_mfma_f32_16x16x32_bf16 v[8:11], v[158:161], v[212:215], v[8:11]
	v_mfma_f32_16x16x32_bf16 v[24:27], v[158:161], v[216:219], v[24:27]
	v_mfma_f32_16x16x32_bf16 v[40:43], v[158:161], v[220:223], v[40:43]
	v_mfma_f32_16x16x32_bf16 v[56:59], v[158:161], v[224:227], v[56:59]
	s_waitcnt lgkmcnt(0)
	v_mfma_f32_16x16x32_bf16 v[12:15], v[162:165], v[212:215], v[12:15]
	v_mfma_f32_16x16x32_bf16 v[28:31], v[162:165], v[216:219], v[28:31]
	v_mfma_f32_16x16x32_bf16 v[44:47], v[162:165], v[220:223], v[44:47]
	v_mfma_f32_16x16x32_bf16 v[60:63], v[162:165], v[224:227], v[60:63]
	s_setprio 0
	s_add_i32 s15, s15, -1
	s_cmp_lg_u32 s15, 0
	s_cbranch_scc1 .Lgo_k_o
	s_nop 7
	v_readlane_b32 s17, v233, 24
	v_readlane_b32 s12, v236, 43
	v_readlane_b32 s13, v236, 44
	s_lshl_b32 s0, s23, 20
	s_add_u32 s12, s12, s0
	s_addc_u32 s13, s13, 0
	s_mov_b64 s[10:11], s[12:13]
	s_cmp_eq_u32 s17, 0
	s_cbranch_scc0 .Lgo_xin_a
	s_add_u32 s10, s36, s0
	s_addc_u32 s11, s37, 0
	s_cmpk_lt_u32 s23, 32
	s_cbranch_scc1 .Lgo_xin_a
	s_sub_u32 s0, s23, 32
	s_lshl_b32 s0, s0, 20
	s_add_u32 s10, s38, s0
	s_addc_u32 s11, s39, 0
.Lgo_xin_a:
	s_lshl_b32 s0, s18, 9
	s_add_u32 s10, s10, s0
	s_addc_u32 s11, s11, 0
	s_add_u32 s12, s12, s0
	s_addc_u32 s13, s13, 0
	v_readlane_b32 s20, v235, 37
	v_readlane_b32 s21, v235, 38
	s_mul_i32 s1, s17, 0x36000
	s_add_u32 s1, s1, 0x4000
	s_add_u32 s1, s1, s0
	s_sub_u32 s0, s23, 32
	s_lshr_b32 s0, s0, 5
	s_cmpk_lt_u32 s23, 32
	s_cselect_b32 s0, 8, s0
	s_mul_i32 s0, s0, 0x6000
	s_add_u32 s1, s1, s0
	s_add_u32 s20, s20, s1
	s_addc_u32 s21, s21, 0
	s_mov_b32 s24, 0x3fd744fd
	s_mov_b32 s25, 0x3fd744fd
	global_load_dwordx4 v[64:67], v90, s[20:21] offset:0
	global_load_dwordx4 v[68:71], v90, s[20:21] offset:16
	global_load_dwordx4 v[72:75], v90, s[20:21] offset:128
	global_load_dwordx4 v[76:79], v90, s[20:21] offset:144
	s_add_u32 s0, s10, 0x0
	s_addc_u32 s1, s11, 0
	global_load_dwordx4 v[196:199], v89, s[0:1] offset:0
	global_load_dwordx4 v[200:203], v89, s[0:1] offset:16
	global_load_dwordx4 v[204:207], v89, s[0:1] offset:128
	global_load_dwordx4 v[208:211], v89, s[0:1] offset:144
	s_add_u32 s0, s10, 0x20000
	s_addc_u32 s1, s11, 0
	global_load_dwordx4 v[212:215], v89, s[0:1] offset:0
	global_load_dwordx4 v[216:219], v89, s[0:1] offset:16
	global_load_dwordx4 v[220:223], v89, s[0:1] offset:128
	global_load_dwordx4 v[224:227], v89, s[0:1] offset:144
	s_add_u32 s0, s10, 0x40000
	s_addc_u32 s1, s11, 0
	global_load_dwordx4 v[80:83], v89, s[0:1] offset:0
	global_load_dwordx4 v[84:87], v89, s[0:1] offset:16
	global_load_dwordx4 v[158:161], v89, s[0:1] offset:128
	global_load_dwordx4 v[162:165], v89, s[0:1] offset:144
	s_waitcnt vmcnt(0)
	s_add_u32 s0, s12, 0x0
	s_addc_u32 s1, s13, 0
	v_pk_mul_f32 v[0:1], v[64:65], v[0:1]
	v_pk_mul_f32 v[2:3], v[66:67], v[2:3]
	v_pk_fma_f32 v[196:197], v[196:197], s[24:25], v[0:1] op_sel_hi:[1,0,1]
	v_pk_fma_f32 v[198:199], v[198:199], s[24:25], v[2:3] op_sel_hi:[1,0,1]
	global_store_dwordx4 v89, v[196:199], s[0:1] offset:0
	v_pk_mul_f32 v[4:5], v[68:69], v[4:5]
	v_pk_mul_f32 v[6:7], v[70:71], v[6:7]
	v_pk_fma_f32 v[200:201], v[200:201], s[24:25], v[4:5] op_sel_hi:[1,0,1]
	v_pk_fma_f32 v[202:203], v[202:203], s[24:25], v[6:7] op_sel_hi:[1,0,1]
	global_store_dwordx4 v89, v[200:203], s[0:1] offset:16
	v_pk_mul_f32 v[8:9], v[72:73], v[8:9]
	v_pk_mul_f32 v[10:11], v[74:75], v[10:11]
	v_pk_fma_f32 v[204:205], v[204:205], s[24:25], v[8:9] op_sel_hi:[1,0,1]
	v_pk_fma_f32 v[206:207], v[206:207], s[24:25], v[10:11] op_sel_hi:[1,0,1]
	global_store_dwordx4 v89, v[204:207], s[0:1] offset:128
	v_pk_mul_f32 v[12:13], v[76:77], v[12:13]
	v_pk_mul_f32 v[14:15], v[78:79], v[14:15]
	v_pk_fma_f32 v[208:209], v[208:209], s[24:25], v[12:13] op_sel_hi:[1,0,1]
	v_pk_fma_f32 v[210:211], v[210:211], s[24:25], v[14:15] op_sel_hi:[1,0,1]
	global_store_dwordx4 v89, v[208:211], s[0:1] offset:144
	s_add_u32 s0, s12, 0x20000
	s_addc_u32 s1, s13, 0
	v_pk_mul_f32 v[16:17], v[64:65], v[16:17]
	v_pk_mul_f32 v[18:19], v[66:67], v[18:19]
	v_pk_fma_f32 v[212:213], v[212:213], s[24:25], v[16:17] op_sel_hi:[1,0,1]
	v_pk_fma_f32 v[214:215], v[214:215], s[24:25], v[18:19] op_sel_hi:[1,0,1]
	global_store_dwordx4 v89, v[212:215], s[0:1] offset:0
	v_pk_mul_f32 v[20:21], v[68:69], v[20:21]
	v_pk_mul_f32 v[22:23], v[70:71], v[22:23]
	v_pk_fma_f32 v[216:217], v[216:217], s[24:25], v[20:21] op_sel_hi:[1,0,1]
	v_pk_fma_f32 v[218:219], v[218:219], s[24:25], v[22:23] op_sel_hi:[1,0,1]
	global_store_dwordx4 v89, v[216:219], s[0:1] offset:16
	v_pk_mul_f32 v[24:25], v[72:73], v[24:25]
	v_pk_mul_f32 v[26:27], v[74:75], v[26:27]
	v_pk_fma_f32 v[220:221], v[220:221], s[24:25], v[24:25] op_sel_hi:[1,0,1]
	v_pk_fma_f32 v[222:223], v[222:223], s[24:25], v[26:27] op_sel_hi:[1,0,1]
	global_store_dwordx4 v89, v[220:223], s[0:1] offset:128
	v_pk_mul_f32 v[28:29], v[76:77], v[28:29]
	v_pk_mul_f32 v[30:31], v[78:79], v[30:31]
	v_pk_fma_f32 v[224:225], v[224:225], s[24:25], v[28:29] op_sel_hi:[1,0,1]
	v_pk_fma_f32 v[226:227], v[226:227], s[24:25], v[30:31] op_sel_hi:[1,0,1]
	global_store_dwordx4 v89, v[224:227], s[0:1] offset:144
	s_add_u32 s0, s12, 0x40000
	s_addc_u32 s1, s13, 0
	v_pk_mul_f32 v[32:33], v[64:65], v[32:33]
	v_pk_mul_f32 v[34:35], v[66:67], v[34:35]
	v_pk_fma_f32 v[80:81], v[80:81], s[24:25], v[32:33] op_sel_hi:[1,0,1]
	v_pk_fma_f32 v[82:83], v[82:83], s[24:25], v[34:35] op_sel_hi:[1,0,1]
	global_store_dwordx4 v89, v[80:83], s[0:1] offset:0
	v_pk_mul_f32 v[36:37], v[68:69], v[36:37]
	v_pk_mul_f32 v[38:39], v[70:71], v[38:39]
	v_pk_fma_f32 v[84:85], v[84:85], s[24:25], v[36:37] op_sel_hi:[1,0,1]
	v_pk_fma_f32 v[86:87], v[86:87], s[24:25], v[38:39] op_sel_hi:[1,0,1]
	global_store_dwordx4 v89, v[84:87], s[0:1] offset:16
	v_pk_mul_f32 v[40:41], v[72:73], v[40:41]
	v_pk_mul_f32 v[42:43], v[74:75], v[42:43]
	v_pk_fma_f32 v[158:159], v[158:159], s[24:25], v[40:41] op_sel_hi:[1,0,1]
	v_pk_fma_f32 v[160:161], v[160:161], s[24:25], v[42:43] op_sel_hi:[1,0,1]
	global_store_dwordx4 v89, v[158:161], s[0:1] offset:128
	v_pk_mul_f32 v[44:45], v[76:77], v[44:45]
	v_pk_mul_f32 v[46:47], v[78:79], v[46:47]
	v_pk_fma_f32 v[162:163], v[162:163], s[24:25], v[44:45] op_sel_hi:[1,0,1]
	v_pk_fma_f32 v[164:165], v[164:165], s[24:25], v[46:47] op_sel_hi:[1,0,1]
	global_store_dwordx4 v89, v[162:165], s[0:1] offset:144
	s_add_u32 s0, s10, 0x60000
	s_addc_u32 s1, s11, 0
	global_load_dwordx4 v[196:199], v89, s[0:1] offset:0
	global_load_dwordx4 v[200:203], v89, s[0:1] offset:16
	global_load_dwordx4 v[204:207], v89, s[0:1] offset:128
	global_load_dwordx4 v[208:211], v89, s[0:1] offset:144
	s_waitcnt vmcnt(0)
	s_add_u32 s0, s12, 0x60000
	s_addc_u32 s1, s13, 0
	v_pk_mul_f32 v[48:49], v[64:65], v[48:49]
	v_pk_mul_f32 v[50:51], v[66:67], v[50:51]
	v_pk_fma_f32 v[196:197], v[196:197], s[24:25], v[48:49] op_sel_hi:[1,0,1]
	v_pk_fma_f32 v[198:199], v[198:199], s[24:25], v[50:51] op_sel_hi:[1,0,1]
	global_store_dwordx4 v89, v[196:199], s[0:1] offset:0
	v_pk_mul_f32 v[52:53], v[68:69], v[52:53]
	v_pk_mul_f32 v[54:55], v[70:71], v[54:55]
	v_pk_fma_f32 v[200:201], v[200:201], s[24:25], v[52:53] op_sel_hi:[1,0,1]
	v_pk_fma_f32 v[202:203], v[202:203], s[24:25], v[54:55] op_sel_hi:[1,0,1]
	global_store_dwordx4 v89, v[200:203], s[0:1] offset:16
	v_pk_mul_f32 v[56:57], v[72:73], v[56:57]
	v_pk_mul_f32 v[58:59], v[74:75], v[58:59]
	v_pk_fma_f32 v[204:205], v[204:205], s[24:25], v[56:57] op_sel_hi:[1,0,1]
	v_pk_fma_f32 v[206:207], v[206:207], s[24:25], v[58:59] op_sel_hi:[1,0,1]
	global_store_dwordx4 v89, v[204:207], s[0:1] offset:128
	v_pk_mul_f32 v[60:61], v[76:77], v[60:61]
	v_pk_mul_f32 v[62:63], v[78:79], v[62:63]
	v_pk_fma_f32 v[208:209], v[208:209], s[24:25], v[60:61] op_sel_hi:[1,0,1]
	v_pk_fma_f32 v[210:211], v[210:211], s[24:25], v[62:63] op_sel_hi:[1,0,1]
	global_store_dwordx4 v89, v[208:211], s[0:1] offset:144
	v_readlane_b32 s17, v233, 24
	v_readlane_b32 s12, v236, 43
	v_readlane_b32 s13, v236, 44
	s_lshl_b32 s0, s23, 20
	s_add_u32 s12, s12, s0
	s_addc_u32 s13, s13, 0
	s_mov_b64 s[10:11], s[12:13]
	s_cmp_eq_u32 s17, 0
	s_cbranch_scc0 .Lgo_xin_b
	s_add_u32 s10, s36, s0
	s_addc_u32 s11, s37, 0
	s_cmpk_lt_u32 s23, 32
	s_cbranch_scc1 .Lgo_xin_b
	s_sub_u32 s0, s23, 32
	s_lshl_b32 s0, s0, 20
	s_add_u32 s10, s38, s0
	s_addc_u32 s11, s39, 0
.Lgo_xin_b:
	s_lshl_b32 s0, s19, 9
	s_add_u32 s10, s10, s0
	s_addc_u32 s11, s11, 0
	s_add_u32 s12, s12, s0
	s_addc_u32 s13, s13, 0
	v_readlane_b32 s20, v235, 37
	v_readlane_b32 s21, v235, 38
	s_mul_i32 s1, s17, 0x36000
	s_add_u32 s1, s1, 0x4000
	s_add_u32 s1, s1, s0
	s_sub_u32 s0, s23, 32
	s_lshr_b32 s0, s0, 5
	s_cmpk_lt_u32 s23, 32
	s_cselect_b32 s0, 8, s0
	s_mul_i32 s0, s0, 0x6000
	s_add_u32 s1, s1, s0
	s_add_u32 s20, s20, s1
	s_addc_u32 s21, s21, 0
	s_mov_b32 s24, 0x3fd744fd
	s_mov_b32 s25, 0x3fd744fd
	global_load_dwordx4 v[196:199], v90, s[20:21] offset:0
	global_load_dwordx4 v[200:203], v90, s[20:21] offset:16
	global_load_dwordx4 v[204:207], v90, s[20:21] offset:128
	global_load_dwordx4 v[208:211], v90, s[20:21] offset:144
	s_add_u32 s0, s10, 0x0
	s_addc_u32 s1, s11, 0
	global_load_dwordx4 v[0:3], v89, s[0:1] offset:0
	global_load_dwordx4 v[4:7], v89, s[0:1] offset:16
	global_load_dwordx4 v[8:11], v89, s[0:1] offset:128
	global_load_dwordx4 v[12:15], v89, s[0:1] offset:144
	s_add_u32 s0, s10, 0x20000
	s_addc_u32 s1, s11, 0
	global_load_dwordx4 v[16:19], v89, s[0:1] offset:0
	global_load_dwordx4 v[20:23], v89, s[0:1] offset:16
	global_load_dwordx4 v[24:27], v89, s[0:1] offset:128
	global_load_dwordx4 v[28:31], v89, s[0:1] offset:144
	s_add_u32 s0, s10, 0x40000
	s_addc_u32 s1, s11, 0
	global_load_dwordx4 v[32:35], v89, s[0:1] offset:0
	global_load_dwordx4 v[36:39], v89, s[0:1] offset:16
	global_load_dwordx4 v[40:43], v89, s[0:1] offset:128
	global_load_dwordx4 v[44:47], v89, s[0:1] offset:144
	s_add_u32 s0, s10, 0x60000
	s_addc_u32 s1, s11, 0
	global_load_dwordx4 v[48:51], v89, s[0:1] offset:0
	global_load_dwordx4 v[52:55], v89, s[0:1] offset:16
	global_load_dwordx4 v[56:59], v89, s[0:1] offset:128
	global_load_dwordx4 v[60:63], v89, s[0:1] offset:144
	s_waitcnt vmcnt(0)
	s_add_u32 s0, s12, 0x0
	s_addc_u32 s1, s13, 0
	v_pk_mul_f32 v[94:95], v[196:197], v[94:95]
	v_pk_mul_f32 v[96:97], v[198:199], v[96:97]
	v_pk_fma_f32 v[0:1], v[0:1], s[24:25], v[94:95] op_sel_hi:[1,0,1]
	v_pk_fma_f32 v[2:3], v[2:3], s[24:25], v[96:97] op_sel_hi:[1,0,1]
	global_store_dwordx4 v89, v[0:3], s[0:1] offset:0
	v_pk_mul_f32 v[98:99], v[200:201], v[98:99]
	v_pk_mul_f32 v[100:101], v[202:203], v[100:101]
	v_pk_fma_f32 v[4:5], v[4:5], s[24:25], v[98:99] op_sel_hi:[1,0,1]
	v_pk_fma_f32 v[6:7], v[6:7], s[24:25], v[100:101] op_sel_hi:[1,0,1]
	global_store_dwordx4 v89, v[4:7], s[0:1] offset:16
	v_pk_mul_f32 v[102:103], v[204:205], v[102:103]
	v_pk_mul_f32 v[104:105], v[206:207], v[104:105]
	v_pk_fma_f32 v[8:9], v[8:9], s[24:25], v[102:103] op_sel_hi:[1,0,1]
	v_pk_fma_f32 v[10:11], v[10:11], s[24:25], v[104:105] op_sel_hi:[1,0,1]
	global_store_dwordx4 v89, v[8:11], s[0:1] offset:128
	v_pk_mul_f32 v[106:107], v[208:209], v[106:107]
	v_pk_mul_f32 v[108:109], v[210:211], v[108:109]
	v_pk_fma_f32 v[12:13], v[12:13], s[24:25], v[106:107] op_sel_hi:[1,0,1]
	v_pk_fma_f32 v[14:15], v[14:15], s[24:25], v[108:109] op_sel_hi:[1,0,1]
	global_store_dwordx4 v89, v[12:15], s[0:1] offset:144
	s_add_u32 s0, s12, 0x20000
	s_addc_u32 s1, s13, 0
	v_pk_mul_f32 v[110:111], v[196:197], v[110:111]
	v_pk_mul_f32 v[112:113], v[198:199], v[112:113]
	v_pk_fma_f32 v[16:17], v[16:17], s[24:25], v[110:111] op_sel_hi:[1,0,1]
	v_pk_fma_f32 v[18:19], v[18:19], s[24:25], v[112:113] op_sel_hi:[1,0,1]
	global_store_dwordx4 v89, v[16:19], s[0:1] offset:0
	v_pk_mul_f32 v[114:115], v[200:201], v[114:115]
	v_pk_mul_f32 v[116:117], v[202:203], v[116:117]
	v_pk_fma_f32 v[20:21], v[20:21], s[24:25], v[114:115] op_sel_hi:[1,0,1]
	v_pk_fma_f32 v[22:23], v[22:23], s[24:25], v[116:117] op_sel_hi:[1,0,1]
	global_store_dwordx4 v89, v[20:23], s[0:1] offset:16
	v_pk_mul_f32 v[118:119], v[204:205], v[118:119]
	v_pk_mul_f32 v[120:121], v[206:207], v[120:121]
	v_pk_fma_f32 v[24:25], v[24:25], s[24:25], v[118:119] op_sel_hi:[1,0,1]
	v_pk_fma_f32 v[26:27], v[26:27], s[24:25], v[120:121] op_sel_hi:[1,0,1]
	global_store_dwordx4 v89, v[24:27], s[0:1] offset:128
	v_pk_mul_f32 v[122:123], v[208:209], v[122:123]
	v_pk_mul_f32 v[124:125], v[210:211], v[124:125]
	v_pk_fma_f32 v[28:29], v[28:29], s[24:25], v[122:123] op_sel_hi:[1,0,1]
	v_pk_fma_f32 v[30:31], v[30:31], s[24:25], v[124:125] op_sel_hi:[1,0,1]
	global_store_dwordx4 v89, v[28:31], s[0:1] offset:144
	s_add_u32 s0, s12, 0x40000
	s_addc_u32 s1, s13, 0
	v_pk_mul_f32 v[126:127], v[196:197], v[126:127]
	v_pk_mul_f32 v[128:129], v[198:199], v[128:129]
	v_pk_fma_f32 v[32:33], v[32:33], s[24:25], v[126:127] op_sel_hi:[1,0,1]
	v_pk_fma_f32 v[34:35], v[34:35], s[24:25], v[128:129] op_sel_hi:[1,0,1]
	global_store_dwordx4 v89, v[32:35], s[0:1] offset:0
	v_pk_mul_f32 v[130:131], v[200:201], v[130:131]
	v_pk_mul_f32 v[132:133], v[202:203], v[132:133]
	v_pk_fma_f32 v[36:37], v[36:37], s[24:25], v[130:131] op_sel_hi:[1,0,1]
	v_pk_fma_f32 v[38:39], v[38:39], s[24:25], v[132:133] op_sel_hi:[1,0,1]
	global_store_dwordx4 v89, v[36:39], s[0:1] offset:16
	v_pk_mul_f32 v[134:135], v[204:205], v[134:135]
	v_pk_mul_f32 v[136:137], v[206:207], v[136:137]
	v_pk_fma_f32 v[40:41], v[40:41], s[24:25], v[134:135] op_sel_hi:[1,0,1]
	v_pk_fma_f32 v[42:43], v[42:43], s[24:25], v[136:137] op_sel_hi:[1,0,1]
	global_store_dwordx4 v89, v[40:43], s[0:1] offset:128
	v_pk_mul_f32 v[138:139], v[208:209], v[138:139]
	v_pk_mul_f32 v[140:141], v[210:211], v[140:141]
	v_pk_fma_f32 v[44:45], v[44:45], s[24:25], v[138:139] op_sel_hi:[1,0,1]
	v_pk_fma_f32 v[46:47], v[46:47], s[24:25], v[140:141] op_sel_hi:[1,0,1]
	global_store_dwordx4 v89, v[44:47], s[0:1] offset:144
	s_add_u32 s0, s12, 0x60000
	s_addc_u32 s1, s13, 0
	v_pk_mul_f32 v[142:143], v[196:197], v[142:143]
	v_pk_mul_f32 v[144:145], v[198:199], v[144:145]
	v_pk_fma_f32 v[48:49], v[48:49], s[24:25], v[142:143] op_sel_hi:[1,0,1]
	v_pk_fma_f32 v[50:51], v[50:51], s[24:25], v[144:145] op_sel_hi:[1,0,1]
	global_store_dwordx4 v89, v[48:51], s[0:1] offset:0
	v_pk_mul_f32 v[146:147], v[200:201], v[146:147]
	v_pk_mul_f32 v[148:149], v[202:203], v[148:149]
	v_pk_fma_f32 v[52:53], v[52:53], s[24:25], v[146:147] op_sel_hi:[1,0,1]
	v_pk_fma_f32 v[54:55], v[54:55], s[24:25], v[148:149] op_sel_hi:[1,0,1]
	global_store_dwordx4 v89, v[52:55], s[0:1] offset:16
	v_pk_mul_f32 v[150:151], v[204:205], v[150:151]
	v_pk_mul_f32 v[152:153], v[206:207], v[152:153]
	v_pk_fma_f32 v[56:57], v[56:57], s[24:25], v[150:151] op_sel_hi:[1,0,1]
	v_pk_fma_f32 v[58:59], v[58:59], s[24:25], v[152:153] op_sel_hi:[1,0,1]
	global_store_dwordx4 v89, v[56:59], s[0:1] offset:128
	v_pk_mul_f32 v[154:155], v[208:209], v[154:155]
	v_pk_mul_f32 v[156:157], v[210:211], v[156:157]
	v_pk_fma_f32 v[60:61], v[60:61], s[24:25], v[154:155] op_sel_hi:[1,0,1]
	v_pk_fma_f32 v[62:63], v[62:63], s[24:25], v[156:157] op_sel_hi:[1,0,1]
	global_store_dwordx4 v89, v[60:63], s[0:1] offset:144
	s_add_u32 s23, s23, 64
	s_add_i32 s16, s16, -1
	s_cmp_eq_u32 s16, 0
	s_cbranch_scc1 .Lgo_exit
	s_cmp_eq_u32 s16, 1
	s_cbranch_scc0 .Lgo_iter
	s_cmpk_lt_u32 s2, 0x100
	s_cbranch_scc0 .Lgo_iter
	s_and_b32 s23, s2, 31
	s_add_u32 s23, s23, 256
	s_lshr_b32 s18, s2, 5
	s_add_u32 s19, s18, 8
	s_branch .Lgo_iter
.Lgo_exit:
	s_waitcnt vmcnt(0)
	s_barrier
	s_branch .LBB0_75

.Lgio_k:
	s_waitcnt vmcnt(0)
	s_barrier
	s_add_i32 m0, s14, 0xc000
	s_nop 0
	global_load_lds_dwordx4 v170, s[6:7]
	s_add_i32 m0, s14, 0xd000
	s_nop 0
	global_load_lds_dwordx4 v171, s[6:7]
	s_add_i32 m0, s14, 0xe000
	s_nop 0
	global_load_lds_dwordx4 v172, s[6:7]
	s_add_i32 m0, s14, 0xf000
	s_nop 0
	global_load_lds_dwordx4 v173, s[6:7]
	ds_read_b128 v[196:199], v228 offset:0
	ds_read_b128 v[200:203], v228 offset:2048
	ds_read_b128 v[204:207], v228 offset:4096
	ds_read_b128 v[208:211], v228 offset:6144
	ds_read_b128 v[212:215], v229 offset:0
	ds_read_b128 v[216:219], v229 offset:2048
	ds_read_b128 v[220:223], v229 offset:4096
	ds_read_b128 v[224:227], v229 offset:6144
	ds_read_b128 v[64:67], v230 offset:16384
	ds_read_b128 v[68:71], v230 offset:18432
	ds_read_b128 v[72:75], v230 offset:20480
	ds_read_b128 v[76:79], v230 offset:22528
	ds_read_b128 v[80:83], v231 offset:16384
	ds_read_b128 v[84:87], v231 offset:18432
	ds_read_b128 v[158:161], v231 offset:20480
	ds_read_b128 v[162:165], v231 offset:22528
	s_waitcnt lgkmcnt(0)
	s_barrier
	s_setprio 1
	s_add_i32 m0, s14, 0x0
	v_mfma_f32_16x16x32_bf16 v[94:97], v[64:67], v[196:199], v[94:97]
	global_load_lds_dwordx4 v166, s[4:5]
	v_mfma_f32_16x16x32_bf16 v[110:113], v[64:67], v[200:203], v[110:113]
	s_add_i32 m0, s14, 0x1000
	v_mfma_f32_16x16x32_bf16 v[126:129], v[64:67], v[204:207], v[126:129]
	global_load_lds_dwordx4 v167, s[4:5]
	v_mfma_f32_16x16x32_bf16 v[142:145], v[64:67], v[208:211], v[142:145]
	ds_read_b128 v[64:67], v230 offset:32768
	s_add_i32 m0, s14, 0x2000
	v_mfma_f32_16x16x32_bf16 v[98:101], v[68:71], v[196:199], v[98:101]
	global_load_lds_dwordx4 v168, s[4:5]
	v_mfma_f32_16x16x32_bf16 v[114:117], v[68:71], v[200:203], v[114:117]
	s_add_i32 m0, s14, 0x3000
	v_mfma_f32_16x16x32_bf16 v[130:133], v[68:71], v[204:207], v[130:133]
	global_load_lds_dwordx4 v169, s[4:5]
	v_mfma_f32_16x16x32_bf16 v[146:149], v[68:71], v[208:211], v[146:149]
	ds_read_b128 v[68:71], v230 offset:34816
	s_add_i32 m0, s14, 0x4000
	v_mfma_f32_16x16x32_bf16 v[102:105], v[72:75], v[196:199], v[102:105]
	global_load_lds_dwordx4 v170, s[8:9]
	v_mfma_f32_16x16x32_bf16 v[118:121], v[72:75], v[200:203], v[118:121]
	s_add_i32 m0, s14, 0x5000
	v_mfma_f32_16x16x32_bf16 v[134:137], v[72:75], v[204:207], v[134:137]
	global_load_lds_dwordx4 v171, s[8:9]
	v_mfma_f32_16x16x32_bf16 v[150:153], v[72:75], v[208:211], v[150:153]
	ds_read_b128 v[72:75], v230 offset:36864
	s_add_i32 m0, s14, 0x6000
	v_mfma_f32_16x16x32_bf16 v[106:109], v[76:79], v[196:199], v[106:109]
	global_load_lds_dwordx4 v172, s[8:9]
	v_mfma_f32_16x16x32_bf16 v[122:125], v[76:79], v[200:203], v[122:125]
	s_add_i32 m0, s14, 0x7000
	v_mfma_f32_16x16x32_bf16 v[138:141], v[76:79], v[204:207], v[138:141]
	global_load_lds_dwordx4 v173, s[8:9]
	v_mfma_f32_16x16x32_bf16 v[154:157], v[76:79], v[208:211], v[154:157]
	ds_read_b128 v[76:79], v230 offset:38912
	v_mfma_f32_16x16x32_bf16 v[94:97], v[80:83], v[212:215], v[94:97]
	v_add_u32_e32 v166, 0x80, v166
	v_mfma_f32_16x16x32_bf16 v[110:113], v[80:83], v[216:219], v[110:113]
	v_add_u32_e32 v167, 0x80, v167
	v_mfma_f32_16x16x32_bf16 v[126:129], v[80:83], v[220:223], v[126:129]
	v_add_u32_e32 v168, 0x80, v168
	v_mfma_f32_16x16x32_bf16 v[142:145], v[80:83], v[224:227], v[142:145]
	v_add_u32_e32 v169, 0x80, v169
	ds_read_b128 v[80:83], v231 offset:32768
	v_mfma_f32_16x16x32_bf16 v[98:101], v[84:87], v[212:215], v[98:101]
	v_add_u32_e32 v170, 0x80, v170
	v_mfma_f32_16x16x32_bf16 v[114:117], v[84:87], v[216:219], v[114:117]
	v_add_u32_e32 v171, 0x80, v171
	v_mfma_f32_16x16x32_bf16 v[130:133], v[84:87], v[220:223], v[130:133]
	v_add_u32_e32 v172, 0x80, v172
	v_mfma_f32_16x16x32_bf16 v[146:149], v[84:87], v[224:227], v[146:149]
	v_add_u32_e32 v173, 0x80, v173
	ds_read_b128 v[84:87], v231 offset:34816
	v_mfma_f32_16x16x32_bf16 v[102:105], v[158:161], v[212:215], v[102:105]
	v_mfma_f32_16x16x32_bf16 v[118:121], v[158:161], v[216:219], v[118:121]
	v_mfma_f32_16x16x32_bf16 v[134:137], v[158:161], v[220:223], v[134:137]
	v_mfma_f32_16x16x32_bf16 v[150:153], v[158:161], v[224:227], v[150:153]
	ds_read_b128 v[158:161], v231 offset:36864
	v_mfma_f32_16x16x32_bf16 v[106:109], v[162:165], v[212:215], v[106:109]
	v_mfma_f32_16x16x32_bf16 v[122:125], v[162:165], v[216:219], v[122:125]
	v_mfma_f32_16x16x32_bf16 v[138:141], v[162:165], v[220:223], v[138:141]
	v_mfma_f32_16x16x32_bf16 v[154:157], v[162:165], v[224:227], v[154:157]
	ds_read_b128 v[162:165], v231 offset:38912
	s_waitcnt lgkmcnt(7)
	v_mfma_f32_16x16x32_bf16 v[0:3], v[64:67], v[196:199], v[0:3]
	v_mfma_f32_16x16x32_bf16 v[16:19], v[64:67], v[200:203], v[16:19]
	v_mfma_f32_16x16x32_bf16 v[32:35], v[64:67], v[204:207], v[32:35]
	v_mfma_f32_16x16x32_bf16 v[48:51], v[64:67], v[208:211], v[48:51]
	s_waitcnt lgkmcnt(6)
	v_mfma_f32_16x16x32_bf16 v[4:7], v[68:71], v[196:199], v[4:7]
	v_mfma_f32_16x16x32_bf16 v[20:23], v[68:71], v[200:203], v[20:23]
	v_mfma_f32_16x16x32_bf16 v[36:39], v[68:71], v[204:207], v[36:39]
	v_mfma_f32_16x16x32_bf16 v[52:55], v[68:71], v[208:211], v[52:55]
	s_waitcnt lgkmcnt(5)
	v_mfma_f32_16x16x32_bf16 v[8:11], v[72:75], v[196:199], v[8:11]
	v_mfma_f32_16x16x32_bf16 v[24:27], v[72:75], v[200:203], v[24:27]
	v_mfma_f32_16x16x32_bf16 v[40:43], v[72:75], v[204:207], v[40:43]
	v_mfma_f32_16x16x32_bf16 v[56:59], v[72:75], v[208:211], v[56:59]
	s_waitcnt lgkmcnt(4)
	v_mfma_f32_16x16x32_bf16 v[12:15], v[76:79], v[196:199], v[12:15]
	v_mfma_f32_16x16x32_bf16 v[28:31], v[76:79], v[200:203], v[28:31]
	v_mfma_f32_16x16x32_bf16 v[44:47], v[76:79], v[204:207], v[44:47]
	v_mfma_f32_16x16x32_bf16 v[60:63], v[76:79], v[208:211], v[60:63]
	s_waitcnt lgkmcnt(3)
	v_mfma_f32_16x16x32_bf16 v[0:3], v[80:83], v[212:215], v[0:3]
	v_mfma_f32_16x16x32_bf16 v[16:19], v[80:83], v[216:219], v[16:19]
	v_mfma_f32_16x16x32_bf16 v[32:35], v[80:83], v[220:223], v[32:35]
	v_mfma_f32_16x16x32_bf16 v[48:51], v[80:83], v[224:227], v[48:51]
	s_waitcnt lgkmcnt(2)
	v_mfma_f32_16x16x32_bf16 v[4:7], v[84:87], v[212:215], v[4:7]
	v_mfma_f32_16x16x32_bf16 v[20:23], v[84:87], v[216:219], v[20:23]
	v_mfma_f32_16x16x32_bf16 v[36:39], v[84:87], v[220:223], v[36:39]
	v_mfma_f32_16x16x32_bf16 v[52:55], v[84:87], v[224:227], v[52:55]
	s_waitcnt lgkmcnt(1)
	v_mfma_f32_16x16x32_bf16 v[8:11], v[158:161], v[212:215], v[8:11]
	v_mfma_f32_16x16x32_bf16 v[24:27], v[158:161], v[216:219], v[24:27]
	v_mfma_f32_16x16x32_bf16 v[40:43], v[158:161], v[220:223], v[40:43]
	v_mfma_f32_16x16x32_bf16 v[56:59], v[158:161], v[224:227], v[56:59]
	s_waitcnt lgkmcnt(0)
	v_mfma_f32_16x16x32_bf16 v[12:15], v[162:165], v[212:215], v[12:15]
	v_mfma_f32_16x16x32_bf16 v[28:31], v[162:165], v[216:219], v[28:31]
	v_mfma_f32_16x16x32_bf16 v[44:47], v[162:165], v[220:223], v[44:47]
	v_mfma_f32_16x16x32_bf16 v[60:63], v[162:165], v[224:227], v[60:63]
	s_setprio 0
	s_waitcnt vmcnt(0)
	s_barrier
	ds_read_b128 v[196:199], v228 offset:0
	ds_read_b128 v[200:203], v228 offset:2048
	ds_read_b128 v[204:207], v228 offset:4096
	ds_read_b128 v[208:211], v228 offset:6144
	ds_read_b128 v[212:215], v229 offset:0
	ds_read_b128 v[216:219], v229 offset:2048
	ds_read_b128 v[220:223], v229 offset:4096
	ds_read_b128 v[224:227], v229 offset:6144
	ds_read_b128 v[64:67], v230 offset:16384
	ds_read_b128 v[68:71], v230 offset:18432
	ds_read_b128 v[72:75], v230 offset:20480
	ds_read_b128 v[76:79], v230 offset:22528
	ds_read_b128 v[80:83], v231 offset:16384
	ds_read_b128 v[84:87], v231 offset:18432
	ds_read_b128 v[158:161], v231 offset:20480
	ds_read_b128 v[162:165], v231 offset:22528
	s_cmp_eq_u32 s15, 1
	s_cselect_b32 s0, 0xfffff000, 0
	s_cselect_b32 s1, -1, 0
	s_cselect_b32 s22, 0x800000, 0
	s_cmp_eq_u32 s16, 1
	s_cselect_b32 s22, 0, s22
	s_add_u32 s6, s6, s0
	s_addc_u32 s7, s7, s1
	s_add_u32 s8, s8, s0
	s_addc_u32 s9, s9, s1
	s_add_u32 s4, s4, s0
	s_addc_u32 s5, s5, s1
	s_add_u32 s4, s4, s22
	s_addc_u32 s5, s5, 0
	s_waitcnt lgkmcnt(0)
	s_barrier
	s_setprio 1
	s_add_i32 m0, s14, 0x0
	v_mfma_f32_16x16x32_bf16 v[94:97], v[64:67], v[196:199], v[94:97]
	global_load_lds_dwordx4 v166, s[4:5]
	v_mfma_f32_16x16x32_bf16 v[110:113], v[64:67], v[200:203], v[110:113]
	s_add_i32 m0, s14, 0x1000
	v_mfma_f32_16x16x32_bf16 v[126:129], v[64:67], v[204:207], v[126:129]
	global_load_lds_dwordx4 v167, s[4:5]
	v_mfma_f32_16x16x32_bf16 v[142:145], v[64:67], v[208:211], v[142:145]
	ds_read_b128 v[64:67], v230 offset:49152
	s_add_i32 m0, s14, 0x2000
	v_mfma_f32_16x16x32_bf16 v[98:101], v[68:71], v[196:199], v[98:101]
	global_load_lds_dwordx4 v168, s[4:5]
	v_mfma_f32_16x16x32_bf16 v[114:117], v[68:71], v[200:203], v[114:117]
	s_add_i32 m0, s14, 0x3000
	v_mfma_f32_16x16x32_bf16 v[130:133], v[68:71], v[204:207], v[130:133]
	global_load_lds_dwordx4 v169, s[4:5]
	v_mfma_f32_16x16x32_bf16 v[146:149], v[68:71], v[208:211], v[146:149]
	ds_read_b128 v[68:71], v230 offset:51200
	s_add_i32 m0, s14, 0x4000
	v_mfma_f32_16x16x32_bf16 v[102:105], v[72:75], v[196:199], v[102:105]
	global_load_lds_dwordx4 v170, s[8:9]
	v_mfma_f32_16x16x32_bf16 v[118:121], v[72:75], v[200:203], v[118:121]
	s_add_i32 m0, s14, 0x5000
	v_mfma_f32_16x16x32_bf16 v[134:137], v[72:75], v[204:207], v[134:137]
	global_load_lds_dwordx4 v171, s[8:9]
	v_mfma_f32_16x16x32_bf16 v[150:153], v[72:75], v[208:211], v[150:153]
	ds_read_b128 v[72:75], v230 offset:53248
	s_add_i32 m0, s14, 0x6000
	v_mfma_f32_16x16x32_bf16 v[106:109], v[76:79], v[196:199], v[106:109]
	global_load_lds_dwordx4 v172, s[8:9]
	v_mfma_f32_16x16x32_bf16 v[122:125], v[76:79], v[200:203], v[122:125]
	s_add_i32 m0, s14, 0x7000
	v_mfma_f32_16x16x32_bf16 v[138:141], v[76:79], v[204:207], v[138:141]
	global_load_lds_dwordx4 v173, s[8:9]
	v_mfma_f32_16x16x32_bf16 v[154:157], v[76:79], v[208:211], v[154:157]
	ds_read_b128 v[76:79], v230 offset:55296
	s_add_i32 m0, s14, 0x8000
	v_mfma_f32_16x16x32_bf16 v[94:97], v[80:83], v[212:215], v[94:97]
	global_load_lds_dwordx4 v170, s[6:7]
	v_mfma_f32_16x16x32_bf16 v[110:113], v[80:83], v[216:219], v[110:113]
	s_add_i32 m0, s14, 0x9000
	v_mfma_f32_16x16x32_bf16 v[126:129], v[80:83], v[220:223], v[126:129]
	global_load_lds_dwordx4 v171, s[6:7]
	v_mfma_f32_16x16x32_bf16 v[142:145], v[80:83], v[224:227], v[142:145]
	ds_read_b128 v[80:83], v231 offset:49152
	s_add_i32 m0, s14, 0xa000
	v_mfma_f32_16x16x32_bf16 v[98:101], v[84:87], v[212:215], v[98:101]
	global_load_lds_dwordx4 v172, s[6:7]
	v_mfma_f32_16x16x32_bf16 v[114:117], v[84:87], v[216:219], v[114:117]
	s_add_i32 m0, s14, 0xb000
	v_mfma_f32_16x16x32_bf16 v[130:133], v[84:87], v[220:223], v[130:133]
	global_load_lds_dwordx4 v173, s[6:7]
	v_mfma_f32_16x16x32_bf16 v[146:149], v[84:87], v[224:227], v[146:149]
	ds_read_b128 v[84:87], v231 offset:51200
	v_mfma_f32_16x16x32_bf16 v[102:105], v[158:161], v[212:215], v[102:105]
	v_add_u32_e32 v166, 0x80, v166
	v_mfma_f32_16x16x32_bf16 v[118:121], v[158:161], v[216:219], v[118:121]
	v_add_u32_e32 v167, 0x80, v167
	v_mfma_f32_16x16x32_bf16 v[134:137], v[158:161], v[220:223], v[134:137]
	v_add_u32_e32 v168, 0x80, v168
	v_mfma_f32_16x16x32_bf16 v[150:153], v[158:161], v[224:227], v[150:153]
	v_add_u32_e32 v169, 0x80, v169
	ds_read_b128 v[158:161], v231 offset:53248
	v_mfma_f32_16x16x32_bf16 v[106:109], v[162:165], v[212:215], v[106:109]
	v_add_u32_e32 v170, 0x80, v170
	v_mfma_f32_16x16x32_bf16 v[122:125], v[162:165], v[216:219], v[122:125]
	v_add_u32_e32 v171, 0x80, v171
	v_mfma_f32_16x16x32_bf16 v[138:141], v[162:165], v[220:223], v[138:141]
	v_add_u32_e32 v172, 0x80, v172
	v_mfma_f32_16x16x32_bf16 v[154:157], v[162:165], v[224:227], v[154:157]
	v_add_u32_e32 v173, 0x80, v173
	ds_read_b128 v[162:165], v231 offset:55296
	s_waitcnt lgkmcnt(7)
	v_mfma_f32_16x16x32_bf16 v[0:3], v[64:67], v[196:199], v[0:3]
	v_mfma_f32_16x16x32_bf16 v[16:19], v[64:67], v[200:203], v[16:19]
	v_mfma_f32_16x16x32_bf16 v[32:35], v[64:67], v[204:207], v[32:35]
	v_mfma_f32_16x16x32_bf16 v[48:51], v[64:67], v[208:211], v[48:51]
	s_waitcnt lgkmcnt(6)
	v_mfma_f32_16x16x32_bf16 v[4:7], v[68:71], v[196:199], v[4:7]
	v_mfma_f32_16x16x32_bf16 v[20:23], v[68:71], v[200:203], v[20:23]
	v_mfma_f32_16x16x32_bf16 v[36:39], v[68:71], v[204:207], v[36:39]
	v_mfma_f32_16x16x32_bf16 v[52:55], v[68:71], v[208:211], v[52:55]
	s_waitcnt lgkmcnt(5)
	v_mfma_f32_16x16x32_bf16 v[8:11], v[72:75], v[196:199], v[8:11]
	v_mfma_f32_16x16x32_bf16 v[24:27], v[72:75], v[200:203], v[24:27]
	v_mfma_f32_16x16x32_bf16 v[40:43], v[72:75], v[204:207], v[40:43]
	v_mfma_f32_16x16x32_bf16 v[56:59], v[72:75], v[208:211], v[56:59]
	s_waitcnt lgkmcnt(4)
	v_mfma_f32_16x16x32_bf16 v[12:15], v[76:79], v[196:199], v[12:15]
	v_mfma_f32_16x16x32_bf16 v[28:31], v[76:79], v[200:203], v[28:31]
	v_mfma_f32_16x16x32_bf16 v[44:47], v[76:79], v[204:207], v[44:47]
	v_mfma_f32_16x16x32_bf16 v[60:63], v[76:79], v[208:211], v[60:63]
	s_waitcnt lgkmcnt(3)
	v_mfma_f32_16x16x32_bf16 v[0:3], v[80:83], v[212:215], v[0:3]
	v_mfma_f32_16x16x32_bf16 v[16:19], v[80:83], v[216:219], v[16:19]
	v_mfma_f32_16x16x32_bf16 v[32:35], v[80:83], v[220:223], v[32:35]
	v_mfma_f32_16x16x32_bf16 v[48:51], v[80:83], v[224:227], v[48:51]
	s_waitcnt lgkmcnt(2)
	v_mfma_f32_16x16x32_bf16 v[4:7], v[84:87], v[212:215], v[4:7]
	v_mfma_f32_16x16x32_bf16 v[20:23], v[84:87], v[216:219], v[20:23]
	v_mfma_f32_16x16x32_bf16 v[36:39], v[84:87], v[220:223], v[36:39]
	v_mfma_f32_16x16x32_bf16 v[52:55], v[84:87], v[224:227], v[52:55]
	s_waitcnt lgkmcnt(1)
	v_mfma_f32_16x16x32_bf16 v[8:11], v[158:161], v[212:215], v[8:11]
	v_mfma_f32_16x16x32_bf16 v[24:27], v[158:161], v[216:219], v[24:27]
	v_mfma_f32_16x16x32_bf16 v[40:43], v[158:161], v[220:223], v[40:43]
	v_mfma_f32_16x16x32_bf16 v[56:59], v[158:161], v[224:227], v[56:59]
	s_waitcnt lgkmcnt(0)
	v_mfma_f32_16x16x32_bf16 v[12:15], v[162:165], v[212:215], v[12:15]
	v_mfma_f32_16x16x32_bf16 v[28:31], v[162:165], v[216:219], v[28:31]
	v_mfma_f32_16x16x32_bf16 v[44:47], v[162:165], v[220:223], v[44:47]
	v_mfma_f32_16x16x32_bf16 v[60:63], v[162:165], v[224:227], v[60:63]
	s_setprio 0
	s_add_i32 s15, s15, -1
	s_cmp_lg_u32 s15, 0
	s_cbranch_scc1 .Lgio_k
	s_nop 7
	s_add_u32 s0, s10, 0x0
	s_addc_u32 s1, s11, 0
	v_cvt_pk_bf16_f32 v196, v0, v1
	v_cvt_pk_bf16_f32 v197, v2, v3
	v_cvt_pk_bf16_f32 v198, v4, v5
	v_cvt_pk_bf16_f32 v199, v6, v7
	global_store_dwordx4 v89, v[196:199], s[0:1] offset:0
	v_cvt_pk_bf16_f32 v200, v8, v9
	v_cvt_pk_bf16_f32 v201, v10, v11
	v_cvt_pk_bf16_f32 v202, v12, v13
	v_cvt_pk_bf16_f32 v203, v14, v15
	global_store_dwordx4 v89, v[200:203], s[0:1] offset:64
	s_add_u32 s0, s10, 0x40000
	s_addc_u32 s1, s11, 0
	v_cvt_pk_bf16_f32 v204, v16, v17
	v_cvt_pk_bf16_f32 v205, v18, v19
	v_cvt_pk_bf16_f32 v206, v20, v21
	v_cvt_pk_bf16_f32 v207, v22, v23
	global_store_dwordx4 v89, v[204:207], s[0:1] offset:0
	v_cvt_pk_bf16_f32 v208, v24, v25
	v_cvt_pk_bf16_f32 v209, v26, v27
	v_cvt_pk_bf16_f32 v210, v28, v29
	v_cvt_pk_bf16_f32 v211, v30, v31
	global_store_dwordx4 v89, v[208:211], s[0:1] offset:64
	s_add_u32 s0, s10, 0x80000
	s_addc_u32 s1, s11, 0
	v_cvt_pk_bf16_f32 v212, v32, v33
	v_cvt_pk_bf16_f32 v213, v34, v35
	v_cvt_pk_bf16_f32 v214, v36, v37
	v_cvt_pk_bf16_f32 v215, v38, v39
	global_store_dwordx4 v89, v[212:215], s[0:1] offset:0
	v_cvt_pk_bf16_f32 v216, v40, v41
	v_cvt_pk_bf16_f32 v217, v42, v43
	v_cvt_pk_bf16_f32 v218, v44, v45
	v_cvt_pk_bf16_f32 v219, v46, v47
	global_store_dwordx4 v89, v[216:219], s[0:1] offset:64
	s_add_u32 s0, s10, 0xc0000
	s_addc_u32 s1, s11, 0
	v_cvt_pk_bf16_f32 v220, v48, v49
	v_cvt_pk_bf16_f32 v221, v50, v51
	v_cvt_pk_bf16_f32 v222, v52, v53
	v_cvt_pk_bf16_f32 v223, v54, v55
	global_store_dwordx4 v89, v[220:223], s[0:1] offset:0
	v_cvt_pk_bf16_f32 v224, v56, v57
	v_cvt_pk_bf16_f32 v225, v58, v59
	v_cvt_pk_bf16_f32 v226, v60, v61
	v_cvt_pk_bf16_f32 v227, v62, v63
	global_store_dwordx4 v89, v[224:227], s[0:1] offset:64
	s_add_u32 s0, s12, 0x0
	s_addc_u32 s1, s13, 0
	v_cvt_pk_bf16_f32 v64, v94, v95
	v_cvt_pk_bf16_f32 v65, v96, v97
	v_cvt_pk_bf16_f32 v66, v98, v99
	v_cvt_pk_bf16_f32 v67, v100, v101
	global_store_dwordx4 v89, v[64:67], s[0:1] offset:0
	v_cvt_pk_bf16_f32 v68, v102, v103
	v_cvt_pk_bf16_f32 v69, v104, v105
	v_cvt_pk_bf16_f32 v70, v106, v107
	v_cvt_pk_bf16_f32 v71, v108, v109
	global_store_dwordx4 v89, v[68:71], s[0:1] offset:64
	s_add_u32 s0, s12, 0x40000
	s_addc_u32 s1, s13, 0
	v_cvt_pk_bf16_f32 v72, v110, v111
	v_cvt_pk_bf16_f32 v73, v112, v113
	v_cvt_pk_bf16_f32 v74, v114, v115
	v_cvt_pk_bf16_f32 v75, v116, v117
	global_store_dwordx4 v89, v[72:75], s[0:1] offset:0
	v_cvt_pk_bf16_f32 v76, v118, v119
	v_cvt_pk_bf16_f32 v77, v120, v121
	v_cvt_pk_bf16_f32 v78, v122, v123
	v_cvt_pk_bf16_f32 v79, v124, v125
	global_store_dwordx4 v89, v[76:79], s[0:1] offset:64
	s_add_u32 s0, s12, 0x80000
	s_addc_u32 s1, s13, 0
	v_cvt_pk_bf16_f32 v80, v126, v127
	v_cvt_pk_bf16_f32 v81, v128, v129
	v_cvt_pk_bf16_f32 v82, v130, v131
	v_cvt_pk_bf16_f32 v83, v132, v133
	global_store_dwordx4 v89, v[80:83], s[0:1] offset:0
	v_cvt_pk_bf16_f32 v84, v134, v135
	v_cvt_pk_bf16_f32 v85, v136, v137
	v_cvt_pk_bf16_f32 v86, v138, v139
	v_cvt_pk_bf16_f32 v87, v140, v141
	global_store_dwordx4 v89, v[84:87], s[0:1] offset:64
	s_add_u32 s0, s12, 0xc0000
	s_addc_u32 s1, s13, 0
	v_cvt_pk_bf16_f32 v158, v142, v143
	v_cvt_pk_bf16_f32 v159, v144, v145
	v_cvt_pk_bf16_f32 v160, v146, v147
	v_cvt_pk_bf16_f32 v161, v148, v149
	global_store_dwordx4 v89, v[158:161], s[0:1] offset:0
	v_cvt_pk_bf16_f32 v162, v150, v151
	v_cvt_pk_bf16_f32 v163, v152, v153
	v_cvt_pk_bf16_f32 v164, v154, v155
	v_cvt_pk_bf16_f32 v165, v156, v157
	global_store_dwordx4 v89, v[162:165], s[0:1] offset:64
	s_add_u32 s10, s10, 0x2000000
	s_addc_u32 s11, s11, 0
	s_add_u32 s12, s12, 0x2000000
	s_addc_u32 s13, s13, 0
	s_add_i32 s16, s16, -1
	s_cmp_lg_u32 s16, 0
	s_cbranch_scc1 .Lgio_tile
	s_waitcnt vmcnt(0)
	s_barrier
	s_branch .LBB0_428

.Lgie_go:
	v_lshrrev_b32_e32 v90, 3, v93
	v_and_b32_e32 v195, 7, v93
	v_bfe_u32 v232, v90, 1, 3
	v_xor_b32_e32 v195, v195, v232
	v_lshlrev_b32_e32 v195, 4, v195
	v_lshl_or_b32 v166, v90, 12, v195
	v_add_u32_e32 v167, 0x20000, v166
	v_add_u32_e32 v168, 0x40000, v166
	v_add_u32_e32 v169, 0x60000, v166
	v_and_b32_e32 v232, 12, v90
	v_lshlrev_b32_e32 v232, 1, v232
	v_and_or_b32 v232, v90, 3, v232
	v_lshrrev_b32_e32 v90, 4, v90
	v_lshl_or_b32 v232, v90, 2, v232
	v_lshl_or_b32 v170, v232, 12, v195
	v_add_u32_e32 v171, 0x20000, v170
	v_add_u32_e32 v172, 0x40000, v170
	v_add_u32_e32 v173, 0x60000, v170
	v_lshrrev_b32_e32 v90, 6, v93
	v_and_b32_e32 v195, 15, v93
	v_readfirstlane_b32 s17, v90
	v_bfe_u32 v232, v93, 4, 2
	s_lshl_b32 s14, s17, 10
	s_lshr_b32 s20, s17, 1
	s_and_b32 s21, s17, 1
	s_lshl_b32 s20, s20, 6
	s_lshl_b32 s21, s21, 6
	v_bfe_u32 v90, v195, 1, 3
	v_xor_b32_e32 v90, v90, v232
	v_lshlrev_b32_e32 v90, 4, v90
	v_add_u32_e32 v229, s20, v195
	v_add_u32_e32 v231, s21, v195
	v_lshl_or_b32 v228, v229, 7, v90
	v_lshl_or_b32 v230, v231, 7, v90
	v_xor_b32_e32 v229, 64, v228
	v_xor_b32_e32 v231, 64, v230
	s_and_b32 s0, s2, 1
	s_lshl_b32 s0, s0, 3
	s_bfe_u32 s1, s2, 0x30003
	s_or_b32 s23, s0, s1
	s_bfe_u32 s0, s2, 0x20001
	s_lshl_b32 s0, s0, 3
	s_lshr_b32 s1, s2, 6
	s_or_b32 s17, s0, s1
	s_lshl_b32 s0, s17, 1
	s_sub_u32 s1, s0, 16
	s_add_u32 s10, s0, 8
	s_add_u32 s11, s17, 32
	s_mov_b32 s18, s17
	s_mov_b32 s19, s11
	s_mov_b32 s24, 0
	s_cmp_ge_u32 s17, 8
	s_cselect_b32 s24, 1, s24
	s_cmp_ge_u32 s17, 16
	s_cselect_b32 s24, 2, s24
	s_cselect_b32 s18, s1, s18
	s_cmp_ge_u32 s17, 20
	s_cselect_b32 s24, 0, s24
	s_cselect_b32 s18, s10, s18
	s_cmp_ge_u32 s17, 24
	s_cselect_b32 s18, s17, s18
	s_add_u32 s12, s18, 1
	s_cmp_ge_u32 s17, 16
	s_cselect_b32 s19, s12, s19
	s_cmp_ge_u32 s17, 24
	s_cselect_b32 s19, s11, s19
	v_readlane_b32 s4, v236, 51
	v_readlane_b32 s5, v236, 52
	v_readlane_b32 s6, v236, 55
	v_readlane_b32 s7, v236, 56
	s_lshl_b32 s0, s23, 19
	s_add_u32 s4, s4, s0
	s_addc_u32 s5, s5, 0
	s_lshl_b32 s0, s19, 19
	s_add_u32 s8, s6, s0
	s_addc_u32 s9, s7, 0
	s_lshl_b32 s0, s18, 19
	s_add_u32 s6, s6, s0
	s_addc_u32 s7, s7, 0
	s_movk_i32 s16, 18
	s_cmpk_lt_u32 s2, 0x120
	s_addc_u32 s16, s16, 0
	s_cmp_eq_u32 s24, 2
	s_cbranch_scc1 .Lgie_lanev
	v_lshrrev_b32_e32 v232, 7, v228
	v_bfe_u32 v195, v93, 4, 2
	v_lshrrev_b32_e32 v90, 6, v93
	v_and_b32_e32 v90, 1, v90
	v_lshlrev_b32_e32 v90, 6, v90
	v_lshl_add_u32 v195, v195, 3, v90
	v_mul_u32_u24_e32 v89, 0x4200, v232
	v_lshl_add_u32 v89, v195, 1, v89
	v_lshlrev_b32_e32 v90, 12, v232
	v_lshl_add_u32 v90, v195, 2, v90
	s_branch .Lgie_lanedone
.Lgie_lanev:
	v_and_b32_e32 v232, 15, v93
	v_lshrrev_b32_e32 v195, 2, v232
	v_lshlrev_b32_e32 v195, 3, v195
	v_and_or_b32 v195, v232, 3, v195
	v_lshrrev_b32_e32 v232, 6, v93
	v_and_b32_e32 v90, 1, v232
	v_lshl_add_u32 v195, v90, 6, v195
	v_lshrrev_b32_e32 v232, 1, v232
	v_lshlrev_b32_e32 v232, 6, v232
	v_bfe_u32 v90, v93, 4, 2
	v_lshl_add_u32 v232, v90, 2, v232
	v_lshlrev_b32_e32 v90, 1, v232
	v_lshl_add_u32 v89, v195, 9, v90
	v_lshl_add_u32 v90, v195, 13, v90
	v_lshlrev_b32_e32 v195, 2, v195
	v_lshl_add_u32 v195, v232, 12, v195
.Lgie_lanedone:
	s_add_i32 m0, s14, 0x0
	s_nop 0
	global_load_lds_dwordx4 v166, s[4:5]
	s_add_i32 m0, s14, 0x1000
	s_nop 0
	global_load_lds_dwordx4 v167, s[4:5]
	s_add_i32 m0, s14, 0x2000
	s_nop 0
	global_load_lds_dwordx4 v168, s[4:5]
	s_add_i32 m0, s14, 0x3000
	s_nop 0
	global_load_lds_dwordx4 v169, s[4:5]
	s_add_i32 m0, s14, 0x4000
	s_nop 0
	global_load_lds_dwordx4 v170, s[8:9]
	s_add_i32 m0, s14, 0x5000
	s_nop 0
	global_load_lds_dwordx4 v171, s[8:9]
	s_add_i32 m0, s14, 0x6000
	s_nop 0
	global_load_lds_dwordx4 v172, s[8:9]
	s_add_i32 m0, s14, 0x7000
	s_nop 0
	global_load_lds_dwordx4 v173, s[8:9]
	s_add_i32 m0, s14, 0x8000
	s_nop 0
	global_load_lds_dwordx4 v170, s[6:7]
	s_add_i32 m0, s14, 0x9000
	s_nop 0
	global_load_lds_dwordx4 v171, s[6:7]
	s_add_i32 m0, s14, 0xa000
	s_nop 0
	global_load_lds_dwordx4 v172, s[6:7]
	s_add_i32 m0, s14, 0xb000
	s_nop 0
	global_load_lds_dwordx4 v173, s[6:7]
	v_add_u32_e32 v166, 0x80, v166
	v_add_u32_e32 v167, 0x80, v167
	v_add_u32_e32 v168, 0x80, v168
	v_add_u32_e32 v169, 0x80, v169
	v_add_u32_e32 v170, 0x80, v170
	v_add_u32_e32 v171, 0x80, v171
	v_add_u32_e32 v172, 0x80, v172
	v_add_u32_e32 v173, 0x80, v173
.Lgie_iter:
	v_mov_b32_e32 v0, 0
	v_mov_b32_e32 v1, 0
	v_mov_b32_e32 v2, 0
	v_mov_b32_e32 v3, 0
	v_mov_b32_e32 v4, 0
	v_mov_b32_e32 v5, 0
	v_mov_b32_e32 v6, 0
	v_mov_b32_e32 v7, 0
	v_mov_b32_e32 v8, 0
	v_mov_b32_e32 v9, 0
	v_mov_b32_e32 v10, 0
	v_mov_b32_e32 v11, 0
	v_mov_b32_e32 v12, 0
	v_mov_b32_e32 v13, 0
	v_mov_b32_e32 v14, 0
	v_mov_b32_e32 v15, 0
	v_mov_b32_e32 v16, 0
	v_mov_b32_e32 v17, 0
	v_mov_b32_e32 v18, 0
	v_mov_b32_e32 v19, 0
	v_mov_b32_e32 v20, 0
	v_mov_b32_e32 v21, 0
	v_mov_b32_e32 v22, 0
	v_mov_b32_e32 v23, 0
	v_mov_b32_e32 v24, 0
	v_mov_b32_e32 v25, 0
	v_mov_b32_e32 v26, 0
	v_mov_b32_e32 v27, 0
	v_mov_b32_e32 v28, 0
	v_mov_b32_e32 v29, 0
	v_mov_b32_e32 v30, 0
	v_mov_b32_e32 v31, 0
	v_mov_b32_e32 v32, 0
	v_mov_b32_e32 v33, 0
	v_mov_b32_e32 v34, 0
	v_mov_b32_e32 v35, 0
	v_mov_b32_e32 v36, 0
	v_mov_b32_e32 v37, 0
	v_mov_b32_e32 v38, 0
	v_mov_b32_e32 v39, 0
	v_mov_b32_e32 v40, 0
	v_mov_b32_e32 v41, 0
	v_mov_b32_e32 v42, 0
	v_mov_b32_e32 v43, 0
	v_mov_b32_e32 v44, 0
	v_mov_b32_e32 v45, 0
	v_mov_b32_e32 v46, 0
	v_mov_b32_e32 v47, 0
	v_mov_b32_e32 v48, 0
	v_mov_b32_e32 v49, 0
	v_mov_b32_e32 v50, 0
	v_mov_b32_e32 v51, 0
	v_mov_b32_e32 v52, 0
	v_mov_b32_e32 v53, 0
	v_mov_b32_e32 v54, 0
	v_mov_b32_e32 v55, 0
	v_mov_b32_e32 v56, 0
	v_mov_b32_e32 v57, 0
	v_mov_b32_e32 v58, 0
	v_mov_b32_e32 v59, 0
	v_mov_b32_e32 v60, 0
	v_mov_b32_e32 v61, 0
	v_mov_b32_e32 v62, 0
	v_mov_b32_e32 v63, 0
	v_mov_b32_e32 v94, 0
	v_mov_b32_e32 v95, 0
	v_mov_b32_e32 v96, 0
	v_mov_b32_e32 v97, 0
	v_mov_b32_e32 v98, 0
	v_mov_b32_e32 v99, 0
	v_mov_b32_e32 v100, 0
	v_mov_b32_e32 v101, 0
	v_mov_b32_e32 v102, 0
	v_mov_b32_e32 v103, 0
	v_mov_b32_e32 v104, 0
	v_mov_b32_e32 v105, 0
	v_mov_b32_e32 v106, 0
	v_mov_b32_e32 v107, 0
	v_mov_b32_e32 v108, 0
	v_mov_b32_e32 v109, 0
	v_mov_b32_e32 v110, 0
	v_mov_b32_e32 v111, 0
	v_mov_b32_e32 v112, 0
	v_mov_b32_e32 v113, 0
	v_mov_b32_e32 v114, 0
	v_mov_b32_e32 v115, 0
	v_mov_b32_e32 v116, 0
	v_mov_b32_e32 v117, 0
	v_mov_b32_e32 v118, 0
	v_mov_b32_e32 v119, 0
	v_mov_b32_e32 v120, 0
	v_mov_b32_e32 v121, 0
	v_mov_b32_e32 v122, 0
	v_mov_b32_e32 v123, 0
	v_mov_b32_e32 v124, 0
	v_mov_b32_e32 v125, 0
	v_mov_b32_e32 v126, 0
	v_mov_b32_e32 v127, 0
	v_mov_b32_e32 v128, 0
	v_mov_b32_e32 v129, 0
	v_mov_b32_e32 v130, 0
	v_mov_b32_e32 v131, 0
	v_mov_b32_e32 v132, 0
	v_mov_b32_e32 v133, 0
	v_mov_b32_e32 v134, 0
	v_mov_b32_e32 v135, 0
	v_mov_b32_e32 v136, 0
	v_mov_b32_e32 v137, 0
	v_mov_b32_e32 v138, 0
	v_mov_b32_e32 v139, 0
	v_mov_b32_e32 v140, 0
	v_mov_b32_e32 v141, 0
	v_mov_b32_e32 v142, 0
	v_mov_b32_e32 v143, 0
	v_mov_b32_e32 v144, 0
	v_mov_b32_e32 v145, 0
	v_mov_b32_e32 v146, 0
	v_mov_b32_e32 v147, 0
	v_mov_b32_e32 v148, 0
	v_mov_b32_e32 v149, 0
	v_mov_b32_e32 v150, 0
	v_mov_b32_e32 v151, 0
	v_mov_b32_e32 v152, 0
	v_mov_b32_e32 v153, 0
	v_mov_b32_e32 v154, 0
	v_mov_b32_e32 v155, 0
	v_mov_b32_e32 v156, 0
	v_mov_b32_e32 v157, 0
	s_cmp_eq_u32 s24, 2
	s_cbranch_scc1 .Lgie_V
	s_movk_i32 s15, 16
.Lgie_k_z:
	s_waitcnt vmcnt(0)
	s_barrier
	s_add_i32 m0, s14, 0xc000
	s_nop 0
	global_load_lds_dwordx4 v170, s[6:7]
	s_add_i32 m0, s14, 0xd000
	s_nop 0
	global_load_lds_dwordx4 v171, s[6:7]
	s_add_i32 m0, s14, 0xe000
	s_nop 0
	global_load_lds_dwordx4 v172, s[6:7]
	s_add_i32 m0, s14, 0xf000
	s_nop 0
	global_load_lds_dwordx4 v173, s[6:7]
	ds_read_b128 v[196:199], v228 offset:0
	ds_read_b128 v[200:203], v228 offset:2048
	ds_read_b128 v[204:207], v228 offset:4096
	ds_read_b128 v[208:211], v228 offset:6144
	ds_read_b128 v[212:215], v229 offset:0
	ds_read_b128 v[216:219], v229 offset:2048
	ds_read_b128 v[220:223], v229 offset:4096
	ds_read_b128 v[224:227], v229 offset:6144
	ds_read_b128 v[64:67], v230 offset:16384
	ds_read_b128 v[68:71], v230 offset:18432
	ds_read_b128 v[72:75], v230 offset:20480
	ds_read_b128 v[76:79], v230 offset:22528
	ds_read_b128 v[80:83], v231 offset:16384
	ds_read_b128 v[84:87], v231 offset:18432
	ds_read_b128 v[158:161], v231 offset:20480
	ds_read_b128 v[162:165], v231 offset:22528
	s_waitcnt lgkmcnt(0)
	s_barrier
	s_setprio 1
	s_add_i32 m0, s14, 0x0
	v_mfma_f32_16x16x32_bf16 v[94:97], v[64:67], v[196:199], v[94:97]
	global_load_lds_dwordx4 v166, s[4:5]
	v_mfma_f32_16x16x32_bf16 v[110:113], v[64:67], v[200:203], v[110:113]
	s_add_i32 m0, s14, 0x1000
	v_mfma_f32_16x16x32_bf16 v[126:129], v[64:67], v[204:207], v[126:129]
	global_load_lds_dwordx4 v167, s[4:5]
	v_mfma_f32_16x16x32_bf16 v[142:145], v[64:67], v[208:211], v[142:145]
	ds_read_b128 v[64:67], v230 offset:32768
	s_add_i32 m0, s14, 0x2000
	v_mfma_f32_16x16x32_bf16 v[98:101], v[68:71], v[196:199], v[98:101]
	global_load_lds_dwordx4 v168, s[4:5]
	v_mfma_f32_16x16x32_bf16 v[114:117], v[68:71], v[200:203], v[114:117]
	s_add_i32 m0, s14, 0x3000
	v_mfma_f32_16x16x32_bf16 v[130:133], v[68:71], v[204:207], v[130:133]
	global_load_lds_dwordx4 v169, s[4:5]
	v_mfma_f32_16x16x32_bf16 v[146:149], v[68:71], v[208:211], v[146:149]
	ds_read_b128 v[68:71], v230 offset:34816
	s_add_i32 m0, s14, 0x4000
	v_mfma_f32_16x16x32_bf16 v[102:105], v[72:75], v[196:199], v[102:105]
	global_load_lds_dwordx4 v170, s[8:9]
	v_mfma_f32_16x16x32_bf16 v[118:121], v[72:75], v[200:203], v[118:121]
	s_add_i32 m0, s14, 0x5000
	v_mfma_f32_16x16x32_bf16 v[134:137], v[72:75], v[204:207], v[134:137]
	global_load_lds_dwordx4 v171, s[8:9]
	v_mfma_f32_16x16x32_bf16 v[150:153], v[72:75], v[208:211], v[150:153]
	ds_read_b128 v[72:75], v230 offset:36864
	s_add_i32 m0, s14, 0x6000
	v_mfma_f32_16x16x32_bf16 v[106:109], v[76:79], v[196:199], v[106:109]
	global_load_lds_dwordx4 v172, s[8:9]
	v_mfma_f32_16x16x32_bf16 v[122:125], v[76:79], v[200:203], v[122:125]
	s_add_i32 m0, s14, 0x7000
	v_mfma_f32_16x16x32_bf16 v[138:141], v[76:79], v[204:207], v[138:141]
	global_load_lds_dwordx4 v173, s[8:9]
	v_mfma_f32_16x16x32_bf16 v[154:157], v[76:79], v[208:211], v[154:157]
	ds_read_b128 v[76:79], v230 offset:38912
	v_mfma_f32_16x16x32_bf16 v[94:97], v[80:83], v[212:215], v[94:97]
	v_add_u32_e32 v166, 0x80, v166
	v_mfma_f32_16x16x32_bf16 v[110:113], v[80:83], v[216:219], v[110:113]
	v_add_u32_e32 v167, 0x80, v167
	v_mfma_f32_16x16x32_bf16 v[126:129], v[80:83], v[220:223], v[126:129]
	v_add_u32_e32 v168, 0x80, v168
	v_mfma_f32_16x16x32_bf16 v[142:145], v[80:83], v[224:227], v[142:145]
	v_add_u32_e32 v169, 0x80, v169
	ds_read_b128 v[80:83], v231 offset:32768
	v_mfma_f32_16x16x32_bf16 v[98:101], v[84:87], v[212:215], v[98:101]
	v_add_u32_e32 v170, 0x80, v170
	v_mfma_f32_16x16x32_bf16 v[114:117], v[84:87], v[216:219], v[114:117]
	v_add_u32_e32 v171, 0x80, v171
	v_mfma_f32_16x16x32_bf16 v[130:133], v[84:87], v[220:223], v[130:133]
	v_add_u32_e32 v172, 0x80, v172
	v_mfma_f32_16x16x32_bf16 v[146:149], v[84:87], v[224:227], v[146:149]
	v_add_u32_e32 v173, 0x80, v173
	ds_read_b128 v[84:87], v231 offset:34816
	v_mfma_f32_16x16x32_bf16 v[102:105], v[158:161], v[212:215], v[102:105]
	v_mfma_f32_16x16x32_bf16 v[118:121], v[158:161], v[216:219], v[118:121]
	v_mfma_f32_16x16x32_bf16 v[134:137], v[158:161], v[220:223], v[134:137]
	v_mfma_f32_16x16x32_bf16 v[150:153], v[158:161], v[224:227], v[150:153]
	ds_read_b128 v[158:161], v231 offset:36864
	v_mfma_f32_16x16x32_bf16 v[106:109], v[162:165], v[212:215], v[106:109]
	v_mfma_f32_16x16x32_bf16 v[122:125], v[162:165], v[216:219], v[122:125]
	v_mfma_f32_16x16x32_bf16 v[138:141], v[162:165], v[220:223], v[138:141]
	v_mfma_f32_16x16x32_bf16 v[154:157], v[162:165], v[224:227], v[154:157]
	ds_read_b128 v[162:165], v231 offset:38912
	s_waitcnt lgkmcnt(7)
	v_mfma_f32_16x16x32_bf16 v[0:3], v[64:67], v[196:199], v[0:3]
	v_mfma_f32_16x16x32_bf16 v[16:19], v[64:67], v[200:203], v[16:19]
	v_mfma_f32_16x16x32_bf16 v[32:35], v[64:67], v[204:207], v[32:35]
	v_mfma_f32_16x16x32_bf16 v[48:51], v[64:67], v[208:211], v[48:51]
	s_waitcnt lgkmcnt(6)
	v_mfma_f32_16x16x32_bf16 v[4:7], v[68:71], v[196:199], v[4:7]
	v_mfma_f32_16x16x32_bf16 v[20:23], v[68:71], v[200:203], v[20:23]
	v_mfma_f32_16x16x32_bf16 v[36:39], v[68:71], v[204:207], v[36:39]
	v_mfma_f32_16x16x32_bf16 v[52:55], v[68:71], v[208:211], v[52:55]
	s_waitcnt lgkmcnt(5)
	v_mfma_f32_16x16x32_bf16 v[8:11], v[72:75], v[196:199], v[8:11]
	v_mfma_f32_16x16x32_bf16 v[24:27], v[72:75], v[200:203], v[24:27]
	v_mfma_f32_16x16x32_bf16 v[40:43], v[72:75], v[204:207], v[40:43]
	v_mfma_f32_16x16x32_bf16 v[56:59], v[72:75], v[208:211], v[56:59]
	s_waitcnt lgkmcnt(4)
	v_mfma_f32_16x16x32_bf16 v[12:15], v[76:79], v[196:199], v[12:15]
	v_mfma_f32_16x16x32_bf16 v[28:31], v[76:79], v[200:203], v[28:31]
	v_mfma_f32_16x16x32_bf16 v[44:47], v[76:79], v[204:207], v[44:47]
	v_mfma_f32_16x16x32_bf16 v[60:63], v[76:79], v[208:211], v[60:63]
	s_waitcnt lgkmcnt(3)
	v_mfma_f32_16x16x32_bf16 v[0:3], v[80:83], v[212:215], v[0:3]
	v_mfma_f32_16x16x32_bf16 v[16:19], v[80:83], v[216:219], v[16:19]
	v_mfma_f32_16x16x32_bf16 v[32:35], v[80:83], v[220:223], v[32:35]
	v_mfma_f32_16x16x32_bf16 v[48:51], v[80:83], v[224:227], v[48:51]
	s_waitcnt lgkmcnt(2)
	v_mfma_f32_16x16x32_bf16 v[4:7], v[84:87], v[212:215], v[4:7]
	v_mfma_f32_16x16x32_bf16 v[20:23], v[84:87], v[216:219], v[20:23]
	v_mfma_f32_16x16x32_bf16 v[36:39], v[84:87], v[220:223], v[36:39]
	v_mfma_f32_16x16x32_bf16 v[52:55], v[84:87], v[224:227], v[52:55]
	s_waitcnt lgkmcnt(1)
	v_mfma_f32_16x16x32_bf16 v[8:11], v[158:161], v[212:215], v[8:11]
	v_mfma_f32_16x16x32_bf16 v[24:27], v[158:161], v[216:219], v[24:27]
	v_mfma_f32_16x16x32_bf16 v[40:43], v[158:161], v[220:223], v[40:43]
	v_mfma_f32_16x16x32_bf16 v[56:59], v[158:161], v[224:227], v[56:59]
	s_waitcnt lgkmcnt(0)
	v_mfma_f32_16x16x32_bf16 v[12:15], v[162:165], v[212:215], v[12:15]
	v_mfma_f32_16x16x32_bf16 v[28:31], v[162:165], v[216:219], v[28:31]
	v_mfma_f32_16x16x32_bf16 v[44:47], v[162:165], v[220:223], v[44:47]
	v_mfma_f32_16x16x32_bf16 v[60:63], v[162:165], v[224:227], v[60:63]
	s_setprio 0
	s_waitcnt vmcnt(0)
	s_barrier
	ds_read_b128 v[196:199], v228 offset:0
	ds_read_b128 v[200:203], v228 offset:2048
	ds_read_b128 v[204:207], v228 offset:4096
	ds_read_b128 v[208:211], v228 offset:6144
	ds_read_b128 v[212:215], v229 offset:0
	ds_read_b128 v[216:219], v229 offset:2048
	ds_read_b128 v[220:223], v229 offset:4096
	ds_read_b128 v[224:227], v229 offset:6144
	ds_read_b128 v[64:67], v230 offset:16384
	ds_read_b128 v[68:71], v230 offset:18432
	ds_read_b128 v[72:75], v230 offset:20480
	ds_read_b128 v[76:79], v230 offset:22528
	ds_read_b128 v[80:83], v231 offset:16384
	ds_read_b128 v[84:87], v231 offset:18432
	ds_read_b128 v[158:161], v231 offset:20480
	ds_read_b128 v[162:165], v231 offset:22528
	s_cmp_lg_u32 s15, 1
	s_cbranch_scc1 .Lhk_done_z
	s_add_u32 s4, s4, 0xfffff000
	s_addc_u32 s5, s5, -1
	s_add_u32 s6, s6, 0xfffff000
	s_addc_u32 s7, s7, -1
	s_add_u32 s8, s8, 0xfffff000
	s_addc_u32 s9, s9, -1
	s_cmp_eq_u32 s16, 1
	s_cbranch_scc1 .Lhk_done_z
	s_cmp_eq_u32 s16, 2
	s_cbranch_scc0 .Lhk_reg_z
	s_cmpk_lt_u32 s2, 0x120
	s_cbranch_scc0 .Lhk_reg_z
	v_readlane_b32 s0, v236, 51
	v_readlane_b32 s1, v236, 52
	s_lshl_b32 s10, s2, 19
	s_add_u32 s4, s0, s10
	s_addc_u32 s5, s1, 0
	s_sub_u32 s4, s4, 0x12000
	s_subb_u32 s5, s5, 0
	v_readlane_b32 s0, v236, 55
	v_readlane_b32 s1, v236, 56
	s_add_u32 s6, s0, 0x1fee000
	s_addc_u32 s7, s1, 0
	s_add_u32 s8, s0, 0x206e000
	s_addc_u32 s9, s1, 0
	s_branch .Lhk_done_z
.Lhk_reg_z:
	s_add_u32 s4, s4, 0x800000
	s_addc_u32 s5, s5, 0
.Lhk_done_z:
	s_waitcnt lgkmcnt(0)
	s_barrier
	s_setprio 1
	s_add_i32 m0, s14, 0x0
	v_mfma_f32_16x16x32_bf16 v[94:97], v[64:67], v[196:199], v[94:97]
	global_load_lds_dwordx4 v166, s[4:5]
	v_mfma_f32_16x16x32_bf16 v[110:113], v[64:67], v[200:203], v[110:113]
	s_add_i32 m0, s14, 0x1000
	v_mfma_f32_16x16x32_bf16 v[126:129], v[64:67], v[204:207], v[126:129]
	global_load_lds_dwordx4 v167, s[4:5]
	v_mfma_f32_16x16x32_bf16 v[142:145], v[64:67], v[208:211], v[142:145]
	ds_read_b128 v[64:67], v230 offset:49152
	s_add_i32 m0, s14, 0x2000
	v_mfma_f32_16x16x32_bf16 v[98:101], v[68:71], v[196:199], v[98:101]
	global_load_lds_dwordx4 v168, s[4:5]
	v_mfma_f32_16x16x32_bf16 v[114:117], v[68:71], v[200:203], v[114:117]
	s_add_i32 m0, s14, 0x3000
	v_mfma_f32_16x16x32_bf16 v[130:133], v[68:71], v[204:207], v[130:133]
	global_load_lds_dwordx4 v169, s[4:5]
	v_mfma_f32_16x16x32_bf16 v[146:149], v[68:71], v[208:211], v[146:149]
	ds_read_b128 v[68:71], v230 offset:51200
	s_add_i32 m0, s14, 0x4000
	v_mfma_f32_16x16x32_bf16 v[102:105], v[72:75], v[196:199], v[102:105]
	global_load_lds_dwordx4 v170, s[8:9]
	v_mfma_f32_16x16x32_bf16 v[118:121], v[72:75], v[200:203], v[118:121]
	s_add_i32 m0, s14, 0x5000
	v_mfma_f32_16x16x32_bf16 v[134:137], v[72:75], v[204:207], v[134:137]
	global_load_lds_dwordx4 v171, s[8:9]
	v_mfma_f32_16x16x32_bf16 v[150:153], v[72:75], v[208:211], v[150:153]
	ds_read_b128 v[72:75], v230 offset:53248
	s_add_i32 m0, s14, 0x6000
	v_mfma_f32_16x16x32_bf16 v[106:109], v[76:79], v[196:199], v[106:109]
	global_load_lds_dwordx4 v172, s[8:9]
	v_mfma_f32_16x16x32_bf16 v[122:125], v[76:79], v[200:203], v[122:125]
	s_add_i32 m0, s14, 0x7000
	v_mfma_f32_16x16x32_bf16 v[138:141], v[76:79], v[204:207], v[138:141]
	global_load_lds_dwordx4 v173, s[8:9]
	v_mfma_f32_16x16x32_bf16 v[154:157], v[76:79], v[208:211], v[154:157]
	ds_read_b128 v[76:79], v230 offset:55296
	s_add_i32 m0, s14, 0x8000
	v_mfma_f32_16x16x32_bf16 v[94:97], v[80:83], v[212:215], v[94:97]
	global_load_lds_dwordx4 v170, s[6:7]
	v_mfma_f32_16x16x32_bf16 v[110:113], v[80:83], v[216:219], v[110:113]
	s_add_i32 m0, s14, 0x9000
	v_mfma_f32_16x16x32_bf16 v[126:129], v[80:83], v[220:223], v[126:129]
	global_load_lds_dwordx4 v171, s[6:7]
	v_mfma_f32_16x16x32_bf16 v[142:145], v[80:83], v[224:227], v[142:145]
	ds_read_b128 v[80:83], v231 offset:49152
	s_add_i32 m0, s14, 0xa000
	v_mfma_f32_16x16x32_bf16 v[98:101], v[84:87], v[212:215], v[98:101]
	global_load_lds_dwordx4 v172, s[6:7]
	v_mfma_f32_16x16x32_bf16 v[114:117], v[84:87], v[216:219], v[114:117]
	s_add_i32 m0, s14, 0xb000
	v_mfma_f32_16x16x32_bf16 v[130:133], v[84:87], v[220:223], v[130:133]
	global_load_lds_dwordx4 v173, s[6:7]
	v_mfma_f32_16x16x32_bf16 v[146:149], v[84:87], v[224:227], v[146:149]
	ds_read_b128 v[84:87], v231 offset:51200
	v_mfma_f32_16x16x32_bf16 v[102:105], v[158:161], v[212:215], v[102:105]
	v_add_u32_e32 v166, 0x80, v166
	v_mfma_f32_16x16x32_bf16 v[118:121], v[158:161], v[216:219], v[118:121]
	v_add_u32_e32 v167, 0x80, v167
	v_mfma_f32_16x16x32_bf16 v[134:137], v[158:161], v[220:223], v[134:137]
	v_add_u32_e32 v168, 0x80, v168
	v_mfma_f32_16x16x32_bf16 v[150:153], v[158:161], v[224:227], v[150:153]
	v_add_u32_e32 v169, 0x80, v169
	ds_read_b128 v[158:161], v231 offset:53248
	v_mfma_f32_16x16x32_bf16 v[106:109], v[162:165], v[212:215], v[106:109]
	v_add_u32_e32 v170, 0x80, v170
	v_mfma_f32_16x16x32_bf16 v[122:125], v[162:165], v[216:219], v[122:125]
	v_add_u32_e32 v171, 0x80, v171
	v_mfma_f32_16x16x32_bf16 v[138:141], v[162:165], v[220:223], v[138:141]
	v_add_u32_e32 v172, 0x80, v172
	v_mfma_f32_16x16x32_bf16 v[154:157], v[162:165], v[224:227], v[154:157]
	v_add_u32_e32 v173, 0x80, v173
	ds_read_b128 v[162:165], v231 offset:55296
	s_waitcnt lgkmcnt(7)
	v_mfma_f32_16x16x32_bf16 v[0:3], v[64:67], v[196:199], v[0:3]
	v_mfma_f32_16x16x32_bf16 v[16:19], v[64:67], v[200:203], v[16:19]
	v_mfma_f32_16x16x32_bf16 v[32:35], v[64:67], v[204:207], v[32:35]
	v_mfma_f32_16x16x32_bf16 v[48:51], v[64:67], v[208:211], v[48:51]
	s_waitcnt lgkmcnt(6)
	v_mfma_f32_16x16x32_bf16 v[4:7], v[68:71], v[196:199], v[4:7]
	v_mfma_f32_16x16x32_bf16 v[20:23], v[68:71], v[200:203], v[20:23]
	v_mfma_f32_16x16x32_bf16 v[36:39], v[68:71], v[204:207], v[36:39]
	v_mfma_f32_16x16x32_bf16 v[52:55], v[68:71], v[208:211], v[52:55]
	s_waitcnt lgkmcnt(5)
	v_mfma_f32_16x16x32_bf16 v[8:11], v[72:75], v[196:199], v[8:11]
	v_mfma_f32_16x16x32_bf16 v[24:27], v[72:75], v[200:203], v[24:27]
	v_mfma_f32_16x16x32_bf16 v[40:43], v[72:75], v[204:207], v[40:43]
	v_mfma_f32_16x16x32_bf16 v[56:59], v[72:75], v[208:211], v[56:59]
	s_waitcnt lgkmcnt(4)
	v_mfma_f32_16x16x32_bf16 v[12:15], v[76:79], v[196:199], v[12:15]
	v_mfma_f32_16x16x32_bf16 v[28:31], v[76:79], v[200:203], v[28:31]
	v_mfma_f32_16x16x32_bf16 v[44:47], v[76:79], v[204:207], v[44:47]
	v_mfma_f32_16x16x32_bf16 v[60:63], v[76:79], v[208:211], v[60:63]
	s_waitcnt lgkmcnt(3)
	v_mfma_f32_16x16x32_bf16 v[0:3], v[80:83], v[212:215], v[0:3]
	v_mfma_f32_16x16x32_bf16 v[16:19], v[80:83], v[216:219], v[16:19]
	v_mfma_f32_16x16x32_bf16 v[32:35], v[80:83], v[220:223], v[32:35]
	v_mfma_f32_16x16x32_bf16 v[48:51], v[80:83], v[224:227], v[48:51]
	s_waitcnt lgkmcnt(2)
	v_mfma_f32_16x16x32_bf16 v[4:7], v[84:87], v[212:215], v[4:7]
	v_mfma_f32_16x16x32_bf16 v[20:23], v[84:87], v[216:219], v[20:23]
	v_mfma_f32_16x16x32_bf16 v[36:39], v[84:87], v[220:223], v[36:39]
	v_mfma_f32_16x16x32_bf16 v[52:55], v[84:87], v[224:227], v[52:55]
	s_waitcnt lgkmcnt(1)
	v_mfma_f32_16x16x32_bf16 v[8:11], v[158:161], v[212:215], v[8:11]
	v_mfma_f32_16x16x32_bf16 v[24:27], v[158:161], v[216:219], v[24:27]
	v_mfma_f32_16x16x32_bf16 v[40:43], v[158:161], v[220:223], v[40:43]
	v_mfma_f32_16x16x32_bf16 v[56:59], v[158:161], v[224:227], v[56:59]
	s_waitcnt lgkmcnt(0)
	v_mfma_f32_16x16x32_bf16 v[12:15], v[162:165], v[212:215], v[12:15]
	v_mfma_f32_16x16x32_bf16 v[28:31], v[162:165], v[216:219], v[28:31]
	v_mfma_f32_16x16x32_bf16 v[44:47], v[162:165], v[220:223], v[44:47]
	v_mfma_f32_16x16x32_bf16 v[60:63], v[162:165], v[224:227], v[60:63]
	s_setprio 0
	s_add_i32 s15, s15, -1
	s_cmp_lg_u32 s15, 0
	s_cbranch_scc1 .Lgie_k_z
	s_nop 7
	v_readlane_b32 s10, v236, 53
	v_readlane_b32 s11, v236, 54
	s_mul_i32 s0, s23, 0x210000
	s_add_u32 s10, s10, s0
	s_addc_u32 s11, s11, 0
	s_lshl_b32 s0, s18, 8
	s_add_u32 s10, s10, s0
	s_addc_u32 s11, s11, 0
	s_add_u32 s0, s10, 0x0
	s_addc_u32 s1, s11, 0
	v_cvt_pk_bf16_f32 v196, v0, v1
	v_cvt_pk_bf16_f32 v197, v2, v3
	v_cvt_pk_bf16_f32 v198, v4, v5
	v_cvt_pk_bf16_f32 v199, v6, v7
	global_store_dwordx4 v89, v[196:199], s[0:1] offset:0
	v_cvt_pk_bf16_f32 v200, v8, v9
	v_cvt_pk_bf16_f32 v201, v10, v11
	v_cvt_pk_bf16_f32 v202, v12, v13
	v_cvt_pk_bf16_f32 v203, v14, v15
	global_store_dwordx4 v89, v[200:203], s[0:1] offset:64
	s_add_u32 s0, s10, 0x42000
	s_addc_u32 s1, s11, 0
	v_cvt_pk_bf16_f32 v204, v16, v17
	v_cvt_pk_bf16_f32 v205, v18, v19
	v_cvt_pk_bf16_f32 v206, v20, v21
	v_cvt_pk_bf16_f32 v207, v22, v23
	global_store_dwordx4 v89, v[204:207], s[0:1] offset:0
	v_cvt_pk_bf16_f32 v208, v24, v25
	v_cvt_pk_bf16_f32 v209, v26, v27
	v_cvt_pk_bf16_f32 v210, v28, v29
	v_cvt_pk_bf16_f32 v211, v30, v31
	global_store_dwordx4 v89, v[208:211], s[0:1] offset:64
	s_add_u32 s0, s10, 0x84000
	s_addc_u32 s1, s11, 0
	v_cvt_pk_bf16_f32 v212, v32, v33
	v_cvt_pk_bf16_f32 v213, v34, v35
	v_cvt_pk_bf16_f32 v214, v36, v37
	v_cvt_pk_bf16_f32 v215, v38, v39
	global_store_dwordx4 v89, v[212:215], s[0:1] offset:0
	v_cvt_pk_bf16_f32 v216, v40, v41
	v_cvt_pk_bf16_f32 v217, v42, v43
	v_cvt_pk_bf16_f32 v218, v44, v45
	v_cvt_pk_bf16_f32 v219, v46, v47
	global_store_dwordx4 v89, v[216:219], s[0:1] offset:64
	s_add_u32 s0, s10, 0xc6000
	s_addc_u32 s1, s11, 0
	v_cvt_pk_bf16_f32 v220, v48, v49
	v_cvt_pk_bf16_f32 v221, v50, v51
	v_cvt_pk_bf16_f32 v222, v52, v53
	v_cvt_pk_bf16_f32 v223, v54, v55
	global_store_dwordx4 v89, v[220:223], s[0:1] offset:0
	v_cvt_pk_bf16_f32 v224, v56, v57
	v_cvt_pk_bf16_f32 v225, v58, v59
	v_cvt_pk_bf16_f32 v226, v60, v61
	v_cvt_pk_bf16_f32 v227, v62, v63
	global_store_dwordx4 v89, v[224:227], s[0:1] offset:64
	s_cmp_eq_u32 s24, 1
	s_cbranch_scc0 .Lgie_nok
	s_cmpk_lt_u32 s23, 32
	s_cbranch_scc0 .Lgie_nok
	v_readlane_b32 s10, v236, 45
	v_readlane_b32 s11, v236, 46
	v_readlane_b32 s0, v233, 25
	s_lshl_b32 s0, s0, 20
	s_add_u32 s10, s10, s0
	s_addc_u32 s11, s11, 0
	s_lshr_b32 s0, s23, 1
	s_lshl_b32 s0, s0, 9
	s_and_b32 s1, s23, 1
	s_lshl_b32 s1, s1, 7
	s_or_b32 s0, s0, s1
	s_lshl_b32 s0, s0, 12
	s_add_u32 s10, s10, s0
	s_addc_u32 s11, s11, 0
	s_lshl_b32 s0, s18, 9
	s_sub_u32 s0, s0, 0x1000
	s_add_u32 s10, s10, s0
	s_addc_u32 s11, s11, 0
	s_add_u32 s0, s10, 0x0
	s_addc_u32 s1, s11, 0
	global_store_dwordx4 v90, v[0:3], s[0:1] offset:0
	global_store_dwordx4 v90, v[4:7], s[0:1] offset:16
	global_store_dwordx4 v90, v[8:11], s[0:1] offset:128
	global_store_dwordx4 v90, v[12:15], s[0:1] offset:144
	s_add_u32 s0, s10, 0x10000
	s_addc_u32 s1, s11, 0
	global_store_dwordx4 v90, v[16:19], s[0:1] offset:0
	global_store_dwordx4 v90, v[20:23], s[0:1] offset:16
	global_store_dwordx4 v90, v[24:27], s[0:1] offset:128
	global_store_dwordx4 v90, v[28:31], s[0:1] offset:144
	s_add_u32 s0, s10, 0x20000
	s_addc_u32 s1, s11, 0
	global_store_dwordx4 v90, v[32:35], s[0:1] offset:0
	global_store_dwordx4 v90, v[36:39], s[0:1] offset:16
	global_store_dwordx4 v90, v[40:43], s[0:1] offset:128
	global_store_dwordx4 v90, v[44:47], s[0:1] offset:144
	s_add_u32 s0, s10, 0x30000
	s_addc_u32 s1, s11, 0
	global_store_dwordx4 v90, v[48:51], s[0:1] offset:0
	global_store_dwordx4 v90, v[52:55], s[0:1] offset:16
	global_store_dwordx4 v90, v[56:59], s[0:1] offset:128
	global_store_dwordx4 v90, v[60:63], s[0:1] offset:144
.Lgie_nok:
	v_readlane_b32 s10, v236, 53
	v_readlane_b32 s11, v236, 54
	s_mul_i32 s0, s23, 0x210000
	s_add_u32 s10, s10, s0
	s_addc_u32 s11, s11, 0
	s_lshl_b32 s0, s19, 8
	s_add_u32 s10, s10, s0
	s_addc_u32 s11, s11, 0
	s_add_u32 s0, s10, 0x0
	s_addc_u32 s1, s11, 0
	v_cvt_pk_bf16_f32 v64, v94, v95
	v_cvt_pk_bf16_f32 v65, v96, v97
	v_cvt_pk_bf16_f32 v66, v98, v99
	v_cvt_pk_bf16_f32 v67, v100, v101
	global_store_dwordx4 v89, v[64:67], s[0:1] offset:0
	v_cvt_pk_bf16_f32 v68, v102, v103
	v_cvt_pk_bf16_f32 v69, v104, v105
	v_cvt_pk_bf16_f32 v70, v106, v107
	v_cvt_pk_bf16_f32 v71, v108, v109
	global_store_dwordx4 v89, v[68:71], s[0:1] offset:64
	s_add_u32 s0, s10, 0x42000
	s_addc_u32 s1, s11, 0
	v_cvt_pk_bf16_f32 v72, v110, v111
	v_cvt_pk_bf16_f32 v73, v112, v113
	v_cvt_pk_bf16_f32 v74, v114, v115
	v_cvt_pk_bf16_f32 v75, v116, v117
	global_store_dwordx4 v89, v[72:75], s[0:1] offset:0
	v_cvt_pk_bf16_f32 v76, v118, v119
	v_cvt_pk_bf16_f32 v77, v120, v121
	v_cvt_pk_bf16_f32 v78, v122, v123
	v_cvt_pk_bf16_f32 v79, v124, v125
	global_store_dwordx4 v89, v[76:79], s[0:1] offset:64
	s_add_u32 s0, s10, 0x84000
	s_addc_u32 s1, s11, 0
	v_cvt_pk_bf16_f32 v80, v126, v127
	v_cvt_pk_bf16_f32 v81, v128, v129
	v_cvt_pk_bf16_f32 v82, v130, v131
	v_cvt_pk_bf16_f32 v83, v132, v133
	global_store_dwordx4 v89, v[80:83], s[0:1] offset:0
	v_cvt_pk_bf16_f32 v84, v134, v135
	v_cvt_pk_bf16_f32 v85, v136, v137
	v_cvt_pk_bf16_f32 v86, v138, v139
	v_cvt_pk_bf16_f32 v87, v140, v141
	global_store_dwordx4 v89, v[84:87], s[0:1] offset:64
	s_add_u32 s0, s10, 0xc6000
	s_addc_u32 s1, s11, 0
	v_cvt_pk_bf16_f32 v158, v142, v143
	v_cvt_pk_bf16_f32 v159, v144, v145
	v_cvt_pk_bf16_f32 v160, v146, v147
	v_cvt_pk_bf16_f32 v161, v148, v149
	global_store_dwordx4 v89, v[158:161], s[0:1] offset:0
	v_cvt_pk_bf16_f32 v162, v150, v151
	v_cvt_pk_bf16_f32 v163, v152, v153
	v_cvt_pk_bf16_f32 v164, v154, v155
	v_cvt_pk_bf16_f32 v165, v156, v157
	global_store_dwordx4 v89, v[162:165], s[0:1] offset:64
	s_branch .Lgie_next
.Lgie_V:
	s_movk_i32 s15, 16
.Lgie_k_v:
	s_waitcnt vmcnt(0)
	s_barrier
	s_add_i32 m0, s14, 0xc000
	s_nop 0
	global_load_lds_dwordx4 v170, s[6:7]
	s_add_i32 m0, s14, 0xd000
	s_nop 0
	global_load_lds_dwordx4 v171, s[6:7]
	s_add_i32 m0, s14, 0xe000
	s_nop 0
	global_load_lds_dwordx4 v172, s[6:7]
	s_add_i32 m0, s14, 0xf000
	s_nop 0
	global_load_lds_dwordx4 v173, s[6:7]
	ds_read_b128 v[196:199], v228 offset:0
	ds_read_b128 v[200:203], v228 offset:2048
	ds_read_b128 v[204:207], v228 offset:4096
	ds_read_b128 v[208:211], v228 offset:6144
	ds_read_b128 v[212:215], v229 offset:0
	ds_read_b128 v[216:219], v229 offset:2048
	ds_read_b128 v[220:223], v229 offset:4096
	ds_read_b128 v[224:227], v229 offset:6144
	ds_read_b128 v[64:67], v230 offset:16384
	ds_read_b128 v[68:71], v230 offset:18432
	ds_read_b128 v[72:75], v230 offset:20480
	ds_read_b128 v[76:79], v230 offset:22528
	ds_read_b128 v[80:83], v231 offset:16384
	ds_read_b128 v[84:87], v231 offset:18432
	ds_read_b128 v[158:161], v231 offset:20480
	ds_read_b128 v[162:165], v231 offset:22528
	s_waitcnt lgkmcnt(0)
	s_barrier
	s_setprio 1
	s_add_i32 m0, s14, 0x0
	v_mfma_f32_16x16x32_bf16 v[94:97], v[196:199], v[64:67], v[94:97]
	global_load_lds_dwordx4 v166, s[4:5]
	v_mfma_f32_16x16x32_bf16 v[110:113], v[200:203], v[64:67], v[110:113]
	s_add_i32 m0, s14, 0x1000
	v_mfma_f32_16x16x32_bf16 v[126:129], v[204:207], v[64:67], v[126:129]
	global_load_lds_dwordx4 v167, s[4:5]
	v_mfma_f32_16x16x32_bf16 v[142:145], v[208:211], v[64:67], v[142:145]
	ds_read_b128 v[64:67], v230 offset:32768
	s_add_i32 m0, s14, 0x2000
	v_mfma_f32_16x16x32_bf16 v[98:101], v[196:199], v[68:71], v[98:101]
	global_load_lds_dwordx4 v168, s[4:5]
	v_mfma_f32_16x16x32_bf16 v[114:117], v[200:203], v[68:71], v[114:117]
	s_add_i32 m0, s14, 0x3000
	v_mfma_f32_16x16x32_bf16 v[130:133], v[204:207], v[68:71], v[130:133]
	global_load_lds_dwordx4 v169, s[4:5]
	v_mfma_f32_16x16x32_bf16 v[146:149], v[208:211], v[68:71], v[146:149]
	ds_read_b128 v[68:71], v230 offset:34816
	s_add_i32 m0, s14, 0x4000
	v_mfma_f32_16x16x32_bf16 v[102:105], v[196:199], v[72:75], v[102:105]
	global_load_lds_dwordx4 v170, s[8:9]
	v_mfma_f32_16x16x32_bf16 v[118:121], v[200:203], v[72:75], v[118:121]
	s_add_i32 m0, s14, 0x5000
	v_mfma_f32_16x16x32_bf16 v[134:137], v[204:207], v[72:75], v[134:137]
	global_load_lds_dwordx4 v171, s[8:9]
	v_mfma_f32_16x16x32_bf16 v[150:153], v[208:211], v[72:75], v[150:153]
	ds_read_b128 v[72:75], v230 offset:36864
	s_add_i32 m0, s14, 0x6000
	v_mfma_f32_16x16x32_bf16 v[106:109], v[196:199], v[76:79], v[106:109]
	global_load_lds_dwordx4 v172, s[8:9]
	v_mfma_f32_16x16x32_bf16 v[122:125], v[200:203], v[76:79], v[122:125]
	s_add_i32 m0, s14, 0x7000
	v_mfma_f32_16x16x32_bf16 v[138:141], v[204:207], v[76:79], v[138:141]
	global_load_lds_dwordx4 v173, s[8:9]
	v_mfma_f32_16x16x32_bf16 v[154:157], v[208:211], v[76:79], v[154:157]
	ds_read_b128 v[76:79], v230 offset:38912
	v_mfma_f32_16x16x32_bf16 v[94:97], v[212:215], v[80:83], v[94:97]
	v_add_u32_e32 v166, 0x80, v166
	v_mfma_f32_16x16x32_bf16 v[110:113], v[216:219], v[80:83], v[110:113]
	v_add_u32_e32 v167, 0x80, v167
	v_mfma_f32_16x16x32_bf16 v[126:129], v[220:223], v[80:83], v[126:129]
	v_add_u32_e32 v168, 0x80, v168
	v_mfma_f32_16x16x32_bf16 v[142:145], v[224:227], v[80:83], v[142:145]
	v_add_u32_e32 v169, 0x80, v169
	ds_read_b128 v[80:83], v231 offset:32768
	v_mfma_f32_16x16x32_bf16 v[98:101], v[212:215], v[84:87], v[98:101]
	v_add_u32_e32 v170, 0x80, v170
	v_mfma_f32_16x16x32_bf16 v[114:117], v[216:219], v[84:87], v[114:117]
	v_add_u32_e32 v171, 0x80, v171
	v_mfma_f32_16x16x32_bf16 v[130:133], v[220:223], v[84:87], v[130:133]
	v_add_u32_e32 v172, 0x80, v172
	v_mfma_f32_16x16x32_bf16 v[146:149], v[224:227], v[84:87], v[146:149]
	v_add_u32_e32 v173, 0x80, v173
	ds_read_b128 v[84:87], v231 offset:34816
	v_mfma_f32_16x16x32_bf16 v[102:105], v[212:215], v[158:161], v[102:105]
	v_mfma_f32_16x16x32_bf16 v[118:121], v[216:219], v[158:161], v[118:121]
	v_mfma_f32_16x16x32_bf16 v[134:137], v[220:223], v[158:161], v[134:137]
	v_mfma_f32_16x16x32_bf16 v[150:153], v[224:227], v[158:161], v[150:153]
	ds_read_b128 v[158:161], v231 offset:36864
	v_mfma_f32_16x16x32_bf16 v[106:109], v[212:215], v[162:165], v[106:109]
	v_mfma_f32_16x16x32_bf16 v[122:125], v[216:219], v[162:165], v[122:125]
	v_mfma_f32_16x16x32_bf16 v[138:141], v[220:223], v[162:165], v[138:141]
	v_mfma_f32_16x16x32_bf16 v[154:157], v[224:227], v[162:165], v[154:157]
	ds_read_b128 v[162:165], v231 offset:38912
	s_waitcnt lgkmcnt(7)
	v_mfma_f32_16x16x32_bf16 v[0:3], v[196:199], v[64:67], v[0:3]
	v_mfma_f32_16x16x32_bf16 v[16:19], v[200:203], v[64:67], v[16:19]
	v_mfma_f32_16x16x32_bf16 v[32:35], v[204:207], v[64:67], v[32:35]
	v_mfma_f32_16x16x32_bf16 v[48:51], v[208:211], v[64:67], v[48:51]
	s_waitcnt lgkmcnt(6)
	v_mfma_f32_16x16x32_bf16 v[4:7], v[196:199], v[68:71], v[4:7]
	v_mfma_f32_16x16x32_bf16 v[20:23], v[200:203], v[68:71], v[20:23]
	v_mfma_f32_16x16x32_bf16 v[36:39], v[204:207], v[68:71], v[36:39]
	v_mfma_f32_16x16x32_bf16 v[52:55], v[208:211], v[68:71], v[52:55]
	s_waitcnt lgkmcnt(5)
	v_mfma_f32_16x16x32_bf16 v[8:11], v[196:199], v[72:75], v[8:11]
	v_mfma_f32_16x16x32_bf16 v[24:27], v[200:203], v[72:75], v[24:27]
	v_mfma_f32_16x16x32_bf16 v[40:43], v[204:207], v[72:75], v[40:43]
	v_mfma_f32_16x16x32_bf16 v[56:59], v[208:211], v[72:75], v[56:59]
	s_waitcnt lgkmcnt(4)
	v_mfma_f32_16x16x32_bf16 v[12:15], v[196:199], v[76:79], v[12:15]
	v_mfma_f32_16x16x32_bf16 v[28:31], v[200:203], v[76:79], v[28:31]
	v_mfma_f32_16x16x32_bf16 v[44:47], v[204:207], v[76:79], v[44:47]
	v_mfma_f32_16x16x32_bf16 v[60:63], v[208:211], v[76:79], v[60:63]
	s_waitcnt lgkmcnt(3)
	v_mfma_f32_16x16x32_bf16 v[0:3], v[212:215], v[80:83], v[0:3]
	v_mfma_f32_16x16x32_bf16 v[16:19], v[216:219], v[80:83], v[16:19]
	v_mfma_f32_16x16x32_bf16 v[32:35], v[220:223], v[80:83], v[32:35]
	v_mfma_f32_16x16x32_bf16 v[48:51], v[224:227], v[80:83], v[48:51]
	s_waitcnt lgkmcnt(2)
	v_mfma_f32_16x16x32_bf16 v[4:7], v[212:215], v[84:87], v[4:7]
	v_mfma_f32_16x16x32_bf16 v[20:23], v[216:219], v[84:87], v[20:23]
	v_mfma_f32_16x16x32_bf16 v[36:39], v[220:223], v[84:87], v[36:39]
	v_mfma_f32_16x16x32_bf16 v[52:55], v[224:227], v[84:87], v[52:55]
	s_waitcnt lgkmcnt(1)
	v_mfma_f32_16x16x32_bf16 v[8:11], v[212:215], v[158:161], v[8:11]
	v_mfma_f32_16x16x32_bf16 v[24:27], v[216:219], v[158:161], v[24:27]
	v_mfma_f32_16x16x32_bf16 v[40:43], v[220:223], v[158:161], v[40:43]
	v_mfma_f32_16x16x32_bf16 v[56:59], v[224:227], v[158:161], v[56:59]
	s_waitcnt lgkmcnt(0)
	v_mfma_f32_16x16x32_bf16 v[12:15], v[212:215], v[162:165], v[12:15]
	v_mfma_f32_16x16x32_bf16 v[28:31], v[216:219], v[162:165], v[28:31]
	v_mfma_f32_16x16x32_bf16 v[44:47], v[220:223], v[162:165], v[44:47]
	v_mfma_f32_16x16x32_bf16 v[60:63], v[224:227], v[162:165], v[60:63]
	s_setprio 0
	s_waitcnt vmcnt(0)
	s_barrier
	ds_read_b128 v[196:199], v228 offset:0
	ds_read_b128 v[200:203], v228 offset:2048
	ds_read_b128 v[204:207], v228 offset:4096
	ds_read_b128 v[208:211], v228 offset:6144
	ds_read_b128 v[212:215], v229 offset:0
	ds_read_b128 v[216:219], v229 offset:2048
	ds_read_b128 v[220:223], v229 offset:4096
	ds_read_b128 v[224:227], v229 offset:6144
	ds_read_b128 v[64:67], v230 offset:16384
	ds_read_b128 v[68:71], v230 offset:18432
	ds_read_b128 v[72:75], v230 offset:20480
	ds_read_b128 v[76:79], v230 offset:22528
	ds_read_b128 v[80:83], v231 offset:16384
	ds_read_b128 v[84:87], v231 offset:18432
	ds_read_b128 v[158:161], v231 offset:20480
	ds_read_b128 v[162:165], v231 offset:22528
	s_cmp_lg_u32 s15, 1
	s_cbranch_scc1 .Lhk_done_v
	s_add_u32 s4, s4, 0xfffff000
	s_addc_u32 s5, s5, -1
	s_add_u32 s6, s6, 0xfffff000
	s_addc_u32 s7, s7, -1
	s_add_u32 s8, s8, 0xfffff000
	s_addc_u32 s9, s9, -1
	s_cmp_eq_u32 s16, 1
	s_cbranch_scc1 .Lhk_done_v
	s_cmp_eq_u32 s16, 2
	s_cbranch_scc0 .Lhk_reg_v
	s_cmpk_lt_u32 s2, 0x120
	s_cbranch_scc0 .Lhk_reg_v
	v_readlane_b32 s0, v236, 51
	v_readlane_b32 s1, v236, 52
	s_lshl_b32 s10, s2, 19
	s_add_u32 s4, s0, s10
	s_addc_u32 s5, s1, 0
	s_sub_u32 s4, s4, 0x12000
	s_subb_u32 s5, s5, 0
	v_readlane_b32 s0, v236, 55
	v_readlane_b32 s1, v236, 56
	s_add_u32 s6, s0, 0x1fee000
	s_addc_u32 s7, s1, 0
	s_add_u32 s8, s0, 0x206e000
	s_addc_u32 s9, s1, 0
	s_branch .Lhk_done_v

.Lhk_done_v:
	s_waitcnt lgkmcnt(0)
	s_barrier
	s_setprio 1
	s_add_i32 m0, s14, 0x0
	v_mfma_f32_16x16x32_bf16 v[94:97], v[196:199], v[64:67], v[94:97]
	global_load_lds_dwordx4 v166, s[4:5]
	v_mfma_f32_16x16x32_bf16 v[110:113], v[200:203], v[64:67], v[110:113]
	s_add_i32 m0, s14, 0x1000
	v_mfma_f32_16x16x32_bf16 v[126:129], v[204:207], v[64:67], v[126:129]
	global_load_lds_dwordx4 v167, s[4:5]
	v_mfma_f32_16x16x32_bf16 v[142:145], v[208:211], v[64:67], v[142:145]
	ds_read_b128 v[64:67], v230 offset:49152
	s_add_i32 m0, s14, 0x2000
	v_mfma_f32_16x16x32_bf16 v[98:101], v[196:199], v[68:71], v[98:101]
	global_load_lds_dwordx4 v168, s[4:5]
	v_mfma_f32_16x16x32_bf16 v[114:117], v[200:203], v[68:71], v[114:117]
	s_add_i32 m0, s14, 0x3000
	v_mfma_f32_16x16x32_bf16 v[130:133], v[204:207], v[68:71], v[130:133]
	global_load_lds_dwordx4 v169, s[4:5]
	v_mfma_f32_16x16x32_bf16 v[146:149], v[208:211], v[68:71], v[146:149]
	ds_read_b128 v[68:71], v230 offset:51200
	s_add_i32 m0, s14, 0x4000
	v_mfma_f32_16x16x32_bf16 v[102:105], v[196:199], v[72:75], v[102:105]
	global_load_lds_dwordx4 v170, s[8:9]
	v_mfma_f32_16x16x32_bf16 v[118:121], v[200:203], v[72:75], v[118:121]
	s_add_i32 m0, s14, 0x5000
	v_mfma_f32_16x16x32_bf16 v[134:137], v[204:207], v[72:75], v[134:137]
	global_load_lds_dwordx4 v171, s[8:9]
	v_mfma_f32_16x16x32_bf16 v[150:153], v[208:211], v[72:75], v[150:153]
	ds_read_b128 v[72:75], v230 offset:53248
	s_add_i32 m0, s14, 0x6000
	v_mfma_f32_16x16x32_bf16 v[106:109], v[196:199], v[76:79], v[106:109]
	global_load_lds_dwordx4 v172, s[8:9]
	v_mfma_f32_16x16x32_bf16 v[122:125], v[200:203], v[76:79], v[122:125]
	s_add_i32 m0, s14, 0x7000
	v_mfma_f32_16x16x32_bf16 v[138:141], v[204:207], v[76:79], v[138:141]
	global_load_lds_dwordx4 v173, s[8:9]
	v_mfma_f32_16x16x32_bf16 v[154:157], v[208:211], v[76:79], v[154:157]
	ds_read_b128 v[76:79], v230 offset:55296
	s_add_i32 m0, s14, 0x8000
	v_mfma_f32_16x16x32_bf16 v[94:97], v[212:215], v[80:83], v[94:97]
	global_load_lds_dwordx4 v170, s[6:7]
	v_mfma_f32_16x16x32_bf16 v[110:113], v[216:219], v[80:83], v[110:113]
	s_add_i32 m0, s14, 0x9000
	v_mfma_f32_16x16x32_bf16 v[126:129], v[220:223], v[80:83], v[126:129]
	global_load_lds_dwordx4 v171, s[6:7]
	v_mfma_f32_16x16x32_bf16 v[142:145], v[224:227], v[80:83], v[142:145]
	ds_read_b128 v[80:83], v231 offset:49152
	s_add_i32 m0, s14, 0xa000
	v_mfma_f32_16x16x32_bf16 v[98:101], v[212:215], v[84:87], v[98:101]
	global_load_lds_dwordx4 v172, s[6:7]
	v_mfma_f32_16x16x32_bf16 v[114:117], v[216:219], v[84:87], v[114:117]
	s_add_i32 m0, s14, 0xb000
	v_mfma_f32_16x16x32_bf16 v[130:133], v[220:223], v[84:87], v[130:133]
	global_load_lds_dwordx4 v173, s[6:7]
	v_mfma_f32_16x16x32_bf16 v[146:149], v[224:227], v[84:87], v[146:149]
	ds_read_b128 v[84:87], v231 offset:51200
	v_mfma_f32_16x16x32_bf16 v[102:105], v[212:215], v[158:161], v[102:105]
	v_add_u32_e32 v166, 0x80, v166
	v_mfma_f32_16x16x32_bf16 v[118:121], v[216:219], v[158:161], v[118:121]
	v_add_u32_e32 v167, 0x80, v167
	v_mfma_f32_16x16x32_bf16 v[134:137], v[220:223], v[158:161], v[134:137]
	v_add_u32_e32 v168, 0x80, v168
	v_mfma_f32_16x16x32_bf16 v[150:153], v[224:227], v[158:161], v[150:153]
	v_add_u32_e32 v169, 0x80, v169
	ds_read_b128 v[158:161], v231 offset:53248
	v_mfma_f32_16x16x32_bf16 v[106:109], v[212:215], v[162:165], v[106:109]
	v_add_u32_e32 v170, 0x80, v170
	v_mfma_f32_16x16x32_bf16 v[122:125], v[216:219], v[162:165], v[122:125]
	v_add_u32_e32 v171, 0x80, v171
	v_mfma_f32_16x16x32_bf16 v[138:141], v[220:223], v[162:165], v[138:141]
	v_add_u32_e32 v172, 0x80, v172
	v_mfma_f32_16x16x32_bf16 v[154:157], v[224:227], v[162:165], v[154:157]
	v_add_u32_e32 v173, 0x80, v173
	ds_read_b128 v[162:165], v231 offset:55296
	s_waitcnt lgkmcnt(7)
	v_mfma_f32_16x16x32_bf16 v[0:3], v[196:199], v[64:67], v[0:3]
	v_mfma_f32_16x16x32_bf16 v[16:19], v[200:203], v[64:67], v[16:19]
	v_mfma_f32_16x16x32_bf16 v[32:35], v[204:207], v[64:67], v[32:35]
	v_mfma_f32_16x16x32_bf16 v[48:51], v[208:211], v[64:67], v[48:51]
	s_waitcnt lgkmcnt(6)
	v_mfma_f32_16x16x32_bf16 v[4:7], v[196:199], v[68:71], v[4:7]
	v_mfma_f32_16x16x32_bf16 v[20:23], v[200:203], v[68:71], v[20:23]
	v_mfma_f32_16x16x32_bf16 v[36:39], v[204:207], v[68:71], v[36:39]
	v_mfma_f32_16x16x32_bf16 v[52:55], v[208:211], v[68:71], v[52:55]
	s_waitcnt lgkmcnt(5)
	v_mfma_f32_16x16x32_bf16 v[8:11], v[196:199], v[72:75], v[8:11]
	v_mfma_f32_16x16x32_bf16 v[24:27], v[200:203], v[72:75], v[24:27]
	v_mfma_f32_16x16x32_bf16 v[40:43], v[204:207], v[72:75], v[40:43]
	v_mfma_f32_16x16x32_bf16 v[56:59], v[208:211], v[72:75], v[56:59]
	s_waitcnt lgkmcnt(4)
	v_mfma_f32_16x16x32_bf16 v[12:15], v[196:199], v[76:79], v[12:15]
	v_mfma_f32_16x16x32_bf16 v[28:31], v[200:203], v[76:79], v[28:31]
	v_mfma_f32_16x16x32_bf16 v[44:47], v[204:207], v[76:79], v[44:47]
	v_mfma_f32_16x16x32_bf16 v[60:63], v[208:211], v[76:79], v[60:63]
	s_waitcnt lgkmcnt(3)
	v_mfma_f32_16x16x32_bf16 v[0:3], v[212:215], v[80:83], v[0:3]
	v_mfma_f32_16x16x32_bf16 v[16:19], v[216:219], v[80:83], v[16:19]
	v_mfma_f32_16x16x32_bf16 v[32:35], v[220:223], v[80:83], v[32:35]
	v_mfma_f32_16x16x32_bf16 v[48:51], v[224:227], v[80:83], v[48:51]
	s_waitcnt lgkmcnt(2)
	v_mfma_f32_16x16x32_bf16 v[4:7], v[212:215], v[84:87], v[4:7]
	v_mfma_f32_16x16x32_bf16 v[20:23], v[216:219], v[84:87], v[20:23]
	v_mfma_f32_16x16x32_bf16 v[36:39], v[220:223], v[84:87], v[36:39]
	v_mfma_f32_16x16x32_bf16 v[52:55], v[224:227], v[84:87], v[52:55]
	s_waitcnt lgkmcnt(1)
	v_mfma_f32_16x16x32_bf16 v[8:11], v[212:215], v[158:161], v[8:11]
	v_mfma_f32_16x16x32_bf16 v[24:27], v[216:219], v[158:161], v[24:27]
	v_mfma_f32_16x16x32_bf16 v[40:43], v[220:223], v[158:161], v[40:43]
	v_mfma_f32_16x16x32_bf16 v[56:59], v[224:227], v[158:161], v[56:59]
	s_waitcnt lgkmcnt(0)
	v_mfma_f32_16x16x32_bf16 v[12:15], v[212:215], v[162:165], v[12:15]
	v_mfma_f32_16x16x32_bf16 v[28:31], v[216:219], v[162:165], v[28:31]
	v_mfma_f32_16x16x32_bf16 v[44:47], v[220:223], v[162:165], v[44:47]
	v_mfma_f32_16x16x32_bf16 v[60:63], v[224:227], v[162:165], v[60:63]
	s_setprio 0
	s_add_i32 s15, s15, -1
	s_cmp_lg_u32 s15, 0
	s_cbranch_scc1 .Lgie_k_v
	s_nop 7
	v_readlane_b32 s10, v235, 29
	v_readlane_b32 s11, v235, 30
	s_lshl_b32 s20, s18, 7
	s_sub_u32 s20, s20, 0x800
	s_cmpk_lt_u32 s23, 32
	s_cbranch_scc0 .Lv_lat_a
	s_lshr_b32 s0, s23, 1
	s_lshl_b32 s1, s0, 10
	s_add_u32 s1, s1, s20
	s_lshl_b32 s1, s1, 8
	s_and_b32 s21, s23, 1
	s_lshl_b32 s21, s21, 7
	s_add_u32 s1, s1, s21
	s_lshl_b32 s1, s1, 1
	s_add_u32 s10, s10, s1
	s_addc_u32 s11, s11, 0
	s_add_u32 s0, s10, 0x0
	s_addc_u32 s1, s11, 0
	v_cvt_pk_bf16_f32 v196, v0, v1
	v_cvt_pk_bf16_f32 v197, v2, v3
	global_store_dwordx2 v89, v[196:197], s[0:1]
	s_add_u32 s0, s10, 0x800
	s_addc_u32 s1, s11, 0
	v_cvt_pk_bf16_f32 v200, v4, v5
	v_cvt_pk_bf16_f32 v201, v6, v7
	global_store_dwordx2 v89, v[200:201], s[0:1]
	s_add_u32 s0, s10, 0x4000
	s_addc_u32 s1, s11, 0
	v_cvt_pk_bf16_f32 v204, v8, v9
	v_cvt_pk_bf16_f32 v205, v10, v11
	global_store_dwordx2 v89, v[204:205], s[0:1]
	s_add_u32 s0, s10, 0x4800
	s_addc_u32 s1, s11, 0
	v_cvt_pk_bf16_f32 v208, v12, v13
	v_cvt_pk_bf16_f32 v209, v14, v15
	global_store_dwordx2 v89, v[208:209], s[0:1]
	s_add_u32 s0, s10, 0x20
	s_addc_u32 s1, s11, 0
	v_cvt_pk_bf16_f32 v212, v16, v17
	v_cvt_pk_bf16_f32 v213, v18, v19
	global_store_dwordx2 v89, v[212:213], s[0:1]
	s_add_u32 s0, s10, 0x820
	s_addc_u32 s1, s11, 0
	v_cvt_pk_bf16_f32 v216, v20, v21
	v_cvt_pk_bf16_f32 v217, v22, v23
	global_store_dwordx2 v89, v[216:217], s[0:1]
	s_add_u32 s0, s10, 0x4020
	s_addc_u32 s1, s11, 0
	v_cvt_pk_bf16_f32 v220, v24, v25
	v_cvt_pk_bf16_f32 v221, v26, v27
	global_store_dwordx2 v89, v[220:221], s[0:1]
	s_add_u32 s0, s10, 0x4820
	s_addc_u32 s1, s11, 0
	v_cvt_pk_bf16_f32 v224, v28, v29
	v_cvt_pk_bf16_f32 v225, v30, v31
	global_store_dwordx2 v89, v[224:225], s[0:1]
	s_add_u32 s0, s10, 0x40
	s_addc_u32 s1, s11, 0
	v_cvt_pk_bf16_f32 v196, v32, v33
	v_cvt_pk_bf16_f32 v197, v34, v35
	global_store_dwordx2 v89, v[196:197], s[0:1]
	s_add_u32 s0, s10, 0x840
	s_addc_u32 s1, s11, 0
	v_cvt_pk_bf16_f32 v200, v36, v37
	v_cvt_pk_bf16_f32 v201, v38, v39
	global_store_dwordx2 v89, v[200:201], s[0:1]
	s_add_u32 s0, s10, 0x4040
	s_addc_u32 s1, s11, 0
	v_cvt_pk_bf16_f32 v204, v40, v41
	v_cvt_pk_bf16_f32 v205, v42, v43
	global_store_dwordx2 v89, v[204:205], s[0:1]
	s_add_u32 s0, s10, 0x4840
	s_addc_u32 s1, s11, 0
	v_cvt_pk_bf16_f32 v208, v44, v45
	v_cvt_pk_bf16_f32 v209, v46, v47
	global_store_dwordx2 v89, v[208:209], s[0:1]
	s_add_u32 s0, s10, 0x60
	s_addc_u32 s1, s11, 0
	v_cvt_pk_bf16_f32 v212, v48, v49
	v_cvt_pk_bf16_f32 v213, v50, v51
	global_store_dwordx2 v89, v[212:213], s[0:1]
	s_add_u32 s0, s10, 0x860
	s_addc_u32 s1, s11, 0
	v_cvt_pk_bf16_f32 v216, v52, v53
	v_cvt_pk_bf16_f32 v217, v54, v55
	global_store_dwordx2 v89, v[216:217], s[0:1]
	s_add_u32 s0, s10, 0x4060
	s_addc_u32 s1, s11, 0
	v_cvt_pk_bf16_f32 v220, v56, v57
	v_cvt_pk_bf16_f32 v221, v58, v59
	global_store_dwordx2 v89, v[220:221], s[0:1]
	s_add_u32 s0, s10, 0x4860
	s_addc_u32 s1, s11, 0
	v_cvt_pk_bf16_f32 v224, v60, v61
	v_cvt_pk_bf16_f32 v225, v62, v63
	global_store_dwordx2 v89, v[224:225], s[0:1]
	v_readlane_b32 s10, v236, 47
	v_readlane_b32 s11, v236, 48
	v_readlane_b32 s0, v233, 25
	s_lshl_b32 s0, s0, 20
	s_add_u32 s10, s10, s0
	s_addc_u32 s11, s11, 0
	s_lshr_b32 s0, s23, 1
	s_lshl_b32 s0, s0, 9
	s_add_u32 s0, s0, s21
	s_lshl_b32 s0, s0, 10
	s_add_u32 s0, s0, s20
	s_lshl_b32 s0, s0, 2
	s_add_u32 s10, s10, s0
	s_addc_u32 s11, s11, 0
	s_add_u32 s0, s10, 0x0
	s_addc_u32 s1, s11, 0
	global_store_dword v195, v0, s[0:1]
	s_add_u32 s0, s10, 0x1000
	s_addc_u32 s1, s11, 0
	global_store_dword v195, v1, s[0:1]
	s_add_u32 s0, s10, 0x2000
	s_addc_u32 s1, s11, 0
	global_store_dword v195, v2, s[0:1]
	s_add_u32 s0, s10, 0x3000
	s_addc_u32 s1, s11, 0
	global_store_dword v195, v3, s[0:1]
	s_add_u32 s0, s10, 0x10
	s_addc_u32 s1, s11, 0
	global_store_dword v195, v4, s[0:1]
	s_add_u32 s0, s10, 0x1010
	s_addc_u32 s1, s11, 0
	global_store_dword v195, v5, s[0:1]
	s_add_u32 s0, s10, 0x2010
	s_addc_u32 s1, s11, 0
	global_store_dword v195, v6, s[0:1]
	s_add_u32 s0, s10, 0x3010
	s_addc_u32 s1, s11, 0
	global_store_dword v195, v7, s[0:1]
	s_add_u32 s0, s10, 0x80
	s_addc_u32 s1, s11, 0
	global_store_dword v195, v8, s[0:1]
	s_add_u32 s0, s10, 0x1080
	s_addc_u32 s1, s11, 0
	global_store_dword v195, v9, s[0:1]
	s_add_u32 s0, s10, 0x2080
	s_addc_u32 s1, s11, 0
	global_store_dword v195, v10, s[0:1]
	s_add_u32 s0, s10, 0x3080
	s_addc_u32 s1, s11, 0
	global_store_dword v195, v11, s[0:1]
	s_add_u32 s0, s10, 0x90
	s_addc_u32 s1, s11, 0
	global_store_dword v195, v12, s[0:1]
	s_add_u32 s0, s10, 0x1090
	s_addc_u32 s1, s11, 0
	global_store_dword v195, v13, s[0:1]
	s_add_u32 s0, s10, 0x2090
	s_addc_u32 s1, s11, 0
	global_store_dword v195, v14, s[0:1]
	s_add_u32 s0, s10, 0x3090
	s_addc_u32 s1, s11, 0
	global_store_dword v195, v15, s[0:1]
	s_add_u32 s0, s10, 0x10000
	s_addc_u32 s1, s11, 0
	global_store_dword v195, v16, s[0:1]
	s_add_u32 s0, s10, 0x11000
	s_addc_u32 s1, s11, 0
	global_store_dword v195, v17, s[0:1]
	s_add_u32 s0, s10, 0x12000
	s_addc_u32 s1, s11, 0
	global_store_dword v195, v18, s[0:1]
	s_add_u32 s0, s10, 0x13000
	s_addc_u32 s1, s11, 0
	global_store_dword v195, v19, s[0:1]
	s_add_u32 s0, s10, 0x10010
	s_addc_u32 s1, s11, 0
	global_store_dword v195, v20, s[0:1]
	s_add_u32 s0, s10, 0x11010
	s_addc_u32 s1, s11, 0
	global_store_dword v195, v21, s[0:1]
	s_add_u32 s0, s10, 0x12010
	s_addc_u32 s1, s11, 0
	global_store_dword v195, v22, s[0:1]
	s_add_u32 s0, s10, 0x13010
	s_addc_u32 s1, s11, 0
	global_store_dword v195, v23, s[0:1]
	s_add_u32 s0, s10, 0x10080
	s_addc_u32 s1, s11, 0
	global_store_dword v195, v24, s[0:1]
	s_add_u32 s0, s10, 0x11080
	s_addc_u32 s1, s11, 0
	global_store_dword v195, v25, s[0:1]
	s_add_u32 s0, s10, 0x12080
	s_addc_u32 s1, s11, 0
	global_store_dword v195, v26, s[0:1]
	s_add_u32 s0, s10, 0x13080
	s_addc_u32 s1, s11, 0
	global_store_dword v195, v27, s[0:1]
	s_add_u32 s0, s10, 0x10090
	s_addc_u32 s1, s11, 0
	global_store_dword v195, v28, s[0:1]
	s_add_u32 s0, s10, 0x11090
	s_addc_u32 s1, s11, 0
	global_store_dword v195, v29, s[0:1]
	s_add_u32 s0, s10, 0x12090
	s_addc_u32 s1, s11, 0
	global_store_dword v195, v30, s[0:1]
	s_add_u32 s0, s10, 0x13090
	s_addc_u32 s1, s11, 0
	global_store_dword v195, v31, s[0:1]
	s_add_u32 s0, s10, 0x20000
	s_addc_u32 s1, s11, 0
	global_store_dword v195, v32, s[0:1]
	s_add_u32 s0, s10, 0x21000
	s_addc_u32 s1, s11, 0
	global_store_dword v195, v33, s[0:1]
	s_add_u32 s0, s10, 0x22000
	s_addc_u32 s1, s11, 0
	global_store_dword v195, v34, s[0:1]
	s_add_u32 s0, s10, 0x23000
	s_addc_u32 s1, s11, 0
	global_store_dword v195, v35, s[0:1]
	s_add_u32 s0, s10, 0x20010
	s_addc_u32 s1, s11, 0
	global_store_dword v195, v36, s[0:1]
	s_add_u32 s0, s10, 0x21010
	s_addc_u32 s1, s11, 0
	global_store_dword v195, v37, s[0:1]
	s_add_u32 s0, s10, 0x22010
	s_addc_u32 s1, s11, 0
	global_store_dword v195, v38, s[0:1]
	s_add_u32 s0, s10, 0x23010
	s_addc_u32 s1, s11, 0
	global_store_dword v195, v39, s[0:1]
	s_add_u32 s0, s10, 0x20080
	s_addc_u32 s1, s11, 0
	global_store_dword v195, v40, s[0:1]
	s_add_u32 s0, s10, 0x21080
	s_addc_u32 s1, s11, 0
	global_store_dword v195, v41, s[0:1]
	s_add_u32 s0, s10, 0x22080
	s_addc_u32 s1, s11, 0
	global_store_dword v195, v42, s[0:1]
	s_add_u32 s0, s10, 0x23080
	s_addc_u32 s1, s11, 0
	global_store_dword v195, v43, s[0:1]
	s_add_u32 s0, s10, 0x20090
	s_addc_u32 s1, s11, 0
	global_store_dword v195, v44, s[0:1]
	s_add_u32 s0, s10, 0x21090
	s_addc_u32 s1, s11, 0
	global_store_dword v195, v45, s[0:1]
	s_add_u32 s0, s10, 0x22090
	s_addc_u32 s1, s11, 0
	global_store_dword v195, v46, s[0:1]
	s_add_u32 s0, s10, 0x23090
	s_addc_u32 s1, s11, 0
	global_store_dword v195, v47, s[0:1]
	s_add_u32 s0, s10, 0x30000
	s_addc_u32 s1, s11, 0
	global_store_dword v195, v48, s[0:1]
	s_add_u32 s0, s10, 0x31000
	s_addc_u32 s1, s11, 0
	global_store_dword v195, v49, s[0:1]
	s_add_u32 s0, s10, 0x32000
	s_addc_u32 s1, s11, 0
	global_store_dword v195, v50, s[0:1]
	s_add_u32 s0, s10, 0x33000
	s_addc_u32 s1, s11, 0
	global_store_dword v195, v51, s[0:1]
	s_add_u32 s0, s10, 0x30010
	s_addc_u32 s1, s11, 0
	global_store_dword v195, v52, s[0:1]
	s_add_u32 s0, s10, 0x31010
	s_addc_u32 s1, s11, 0
	global_store_dword v195, v53, s[0:1]
	s_add_u32 s0, s10, 0x32010
	s_addc_u32 s1, s11, 0
	global_store_dword v195, v54, s[0:1]
	s_add_u32 s0, s10, 0x33010
	s_addc_u32 s1, s11, 0
	global_store_dword v195, v55, s[0:1]
	s_add_u32 s0, s10, 0x30080
	s_addc_u32 s1, s11, 0
	global_store_dword v195, v56, s[0:1]
	s_add_u32 s0, s10, 0x31080
	s_addc_u32 s1, s11, 0
	global_store_dword v195, v57, s[0:1]
	s_add_u32 s0, s10, 0x32080
	s_addc_u32 s1, s11, 0
	global_store_dword v195, v58, s[0:1]
	s_add_u32 s0, s10, 0x33080
	s_addc_u32 s1, s11, 0
	global_store_dword v195, v59, s[0:1]
	s_add_u32 s0, s10, 0x30090
	s_addc_u32 s1, s11, 0
	global_store_dword v195, v60, s[0:1]
	s_add_u32 s0, s10, 0x31090
	s_addc_u32 s1, s11, 0
	global_store_dword v195, v61, s[0:1]
	s_add_u32 s0, s10, 0x32090
	s_addc_u32 s1, s11, 0
	global_store_dword v195, v62, s[0:1]
	s_add_u32 s0, s10, 0x33090
	s_addc_u32 s1, s11, 0
	global_store_dword v195, v63, s[0:1]
	s_branch .Lv_done_a
.Lv_lat_a:
	s_sub_u32 s0, s23, 32
	s_lshr_b32 s1, s0, 5
	s_lshl_b32 s1, s1, 10
	s_add_u32 s1, s1, s20
	s_lshl_b32 s1, s1, 12
	s_and_b32 s0, s0, 31
	s_lshl_b32 s0, s0, 7
	s_add_u32 s1, s1, s0
	s_lshl_b32 s1, s1, 1
	s_add_u32 s10, s10, s1
	s_addc_u32 s11, s11, 0
	s_add_u32 s10, s10, 0x800000
	s_addc_u32 s11, s11, 0
	s_add_u32 s0, s10, 0x0
	s_addc_u32 s1, s11, 0
	v_cvt_pk_bf16_f32 v196, v0, v1
	v_cvt_pk_bf16_f32 v197, v2, v3
	global_store_dwordx2 v90, v[196:197], s[0:1]
	s_add_u32 s0, s10, 0x8000
	s_addc_u32 s1, s11, 0
	v_cvt_pk_bf16_f32 v200, v4, v5
	v_cvt_pk_bf16_f32 v201, v6, v7
	global_store_dwordx2 v90, v[200:201], s[0:1]
	s_add_u32 s0, s10, 0x40000
	s_addc_u32 s1, s11, 0
	v_cvt_pk_bf16_f32 v204, v8, v9
	v_cvt_pk_bf16_f32 v205, v10, v11
	global_store_dwordx2 v90, v[204:205], s[0:1]
	s_add_u32 s0, s10, 0x48000
	s_addc_u32 s1, s11, 0
	v_cvt_pk_bf16_f32 v208, v12, v13
	v_cvt_pk_bf16_f32 v209, v14, v15
	global_store_dwordx2 v90, v[208:209], s[0:1]
	s_add_u32 s0, s10, 0x20
	s_addc_u32 s1, s11, 0
	v_cvt_pk_bf16_f32 v212, v16, v17
	v_cvt_pk_bf16_f32 v213, v18, v19
	global_store_dwordx2 v90, v[212:213], s[0:1]
	s_add_u32 s0, s10, 0x8020
	s_addc_u32 s1, s11, 0
	v_cvt_pk_bf16_f32 v216, v20, v21
	v_cvt_pk_bf16_f32 v217, v22, v23
	global_store_dwordx2 v90, v[216:217], s[0:1]
	s_add_u32 s0, s10, 0x40020
	s_addc_u32 s1, s11, 0
	v_cvt_pk_bf16_f32 v220, v24, v25
	v_cvt_pk_bf16_f32 v221, v26, v27
	global_store_dwordx2 v90, v[220:221], s[0:1]
	s_add_u32 s0, s10, 0x48020
	s_addc_u32 s1, s11, 0
	v_cvt_pk_bf16_f32 v224, v28, v29
	v_cvt_pk_bf16_f32 v225, v30, v31
	global_store_dwordx2 v90, v[224:225], s[0:1]
	s_add_u32 s0, s10, 0x40
	s_addc_u32 s1, s11, 0
	v_cvt_pk_bf16_f32 v196, v32, v33
	v_cvt_pk_bf16_f32 v197, v34, v35
	global_store_dwordx2 v90, v[196:197], s[0:1]
	s_add_u32 s0, s10, 0x8040
	s_addc_u32 s1, s11, 0
	v_cvt_pk_bf16_f32 v200, v36, v37
	v_cvt_pk_bf16_f32 v201, v38, v39
	global_store_dwordx2 v90, v[200:201], s[0:1]
	s_add_u32 s0, s10, 0x40040
	s_addc_u32 s1, s11, 0
	v_cvt_pk_bf16_f32 v204, v40, v41
	v_cvt_pk_bf16_f32 v205, v42, v43
	global_store_dwordx2 v90, v[204:205], s[0:1]
	s_add_u32 s0, s10, 0x48040
	s_addc_u32 s1, s11, 0
	v_cvt_pk_bf16_f32 v208, v44, v45
	v_cvt_pk_bf16_f32 v209, v46, v47
	global_store_dwordx2 v90, v[208:209], s[0:1]
	s_add_u32 s0, s10, 0x60
	s_addc_u32 s1, s11, 0
	v_cvt_pk_bf16_f32 v212, v48, v49
	v_cvt_pk_bf16_f32 v213, v50, v51
	global_store_dwordx2 v90, v[212:213], s[0:1]
	s_add_u32 s0, s10, 0x8060
	s_addc_u32 s1, s11, 0
	v_cvt_pk_bf16_f32 v216, v52, v53
	v_cvt_pk_bf16_f32 v217, v54, v55
	global_store_dwordx2 v90, v[216:217], s[0:1]
	s_add_u32 s0, s10, 0x40060
	s_addc_u32 s1, s11, 0
	v_cvt_pk_bf16_f32 v220, v56, v57
	v_cvt_pk_bf16_f32 v221, v58, v59
	global_store_dwordx2 v90, v[220:221], s[0:1]
	s_add_u32 s0, s10, 0x48060
	s_addc_u32 s1, s11, 0
	v_cvt_pk_bf16_f32 v224, v60, v61
	v_cvt_pk_bf16_f32 v225, v62, v63
	global_store_dwordx2 v90, v[224:225], s[0:1]
.Lv_done_a:
	v_readlane_b32 s10, v235, 29
	v_readlane_b32 s11, v235, 30
	s_lshl_b32 s20, s19, 7
	s_sub_u32 s20, s20, 0x800
	s_cmpk_lt_u32 s23, 32
	s_cbranch_scc0 .Lv_lat_b
	s_lshr_b32 s0, s23, 1
	s_lshl_b32 s1, s0, 10
	s_add_u32 s1, s1, s20
	s_lshl_b32 s1, s1, 8
	s_and_b32 s21, s23, 1
	s_lshl_b32 s21, s21, 7
	s_add_u32 s1, s1, s21
	s_lshl_b32 s1, s1, 1
	s_add_u32 s10, s10, s1
	s_addc_u32 s11, s11, 0
	s_add_u32 s0, s10, 0x0
	s_addc_u32 s1, s11, 0
	v_cvt_pk_bf16_f32 v64, v94, v95
	v_cvt_pk_bf16_f32 v65, v96, v97
	global_store_dwordx2 v89, v[64:65], s[0:1]
	s_add_u32 s0, s10, 0x800
	s_addc_u32 s1, s11, 0
	v_cvt_pk_bf16_f32 v68, v98, v99
	v_cvt_pk_bf16_f32 v69, v100, v101
	global_store_dwordx2 v89, v[68:69], s[0:1]
	s_add_u32 s0, s10, 0x4000
	s_addc_u32 s1, s11, 0
	v_cvt_pk_bf16_f32 v72, v102, v103
	v_cvt_pk_bf16_f32 v73, v104, v105
	global_store_dwordx2 v89, v[72:73], s[0:1]
	s_add_u32 s0, s10, 0x4800
	s_addc_u32 s1, s11, 0
	v_cvt_pk_bf16_f32 v76, v106, v107
	v_cvt_pk_bf16_f32 v77, v108, v109
	global_store_dwordx2 v89, v[76:77], s[0:1]
	s_add_u32 s0, s10, 0x20
	s_addc_u32 s1, s11, 0
	v_cvt_pk_bf16_f32 v80, v110, v111
	v_cvt_pk_bf16_f32 v81, v112, v113
	global_store_dwordx2 v89, v[80:81], s[0:1]
	s_add_u32 s0, s10, 0x820
	s_addc_u32 s1, s11, 0
	v_cvt_pk_bf16_f32 v84, v114, v115
	v_cvt_pk_bf16_f32 v85, v116, v117
	global_store_dwordx2 v89, v[84:85], s[0:1]
	s_add_u32 s0, s10, 0x4020
	s_addc_u32 s1, s11, 0
	v_cvt_pk_bf16_f32 v158, v118, v119
	v_cvt_pk_bf16_f32 v159, v120, v121
	global_store_dwordx2 v89, v[158:159], s[0:1]
	s_add_u32 s0, s10, 0x4820
	s_addc_u32 s1, s11, 0
	v_cvt_pk_bf16_f32 v162, v122, v123
	v_cvt_pk_bf16_f32 v163, v124, v125
	global_store_dwordx2 v89, v[162:163], s[0:1]
	s_add_u32 s0, s10, 0x40
	s_addc_u32 s1, s11, 0
	v_cvt_pk_bf16_f32 v64, v126, v127
	v_cvt_pk_bf16_f32 v65, v128, v129
	global_store_dwordx2 v89, v[64:65], s[0:1]
	s_add_u32 s0, s10, 0x840
	s_addc_u32 s1, s11, 0
	v_cvt_pk_bf16_f32 v68, v130, v131
	v_cvt_pk_bf16_f32 v69, v132, v133
	global_store_dwordx2 v89, v[68:69], s[0:1]
	s_add_u32 s0, s10, 0x4040
	s_addc_u32 s1, s11, 0
	v_cvt_pk_bf16_f32 v72, v134, v135
	v_cvt_pk_bf16_f32 v73, v136, v137
	global_store_dwordx2 v89, v[72:73], s[0:1]
	s_add_u32 s0, s10, 0x4840
	s_addc_u32 s1, s11, 0
	v_cvt_pk_bf16_f32 v76, v138, v139
	v_cvt_pk_bf16_f32 v77, v140, v141
	global_store_dwordx2 v89, v[76:77], s[0:1]
	s_add_u32 s0, s10, 0x60
	s_addc_u32 s1, s11, 0
	v_cvt_pk_bf16_f32 v80, v142, v143
	v_cvt_pk_bf16_f32 v81, v144, v145
	global_store_dwordx2 v89, v[80:81], s[0:1]
	s_add_u32 s0, s10, 0x860
	s_addc_u32 s1, s11, 0
	v_cvt_pk_bf16_f32 v84, v146, v147
	v_cvt_pk_bf16_f32 v85, v148, v149
	global_store_dwordx2 v89, v[84:85], s[0:1]
	s_add_u32 s0, s10, 0x4060
	s_addc_u32 s1, s11, 0
	v_cvt_pk_bf16_f32 v158, v150, v151
	v_cvt_pk_bf16_f32 v159, v152, v153
	global_store_dwordx2 v89, v[158:159], s[0:1]
	s_add_u32 s0, s10, 0x4860
	s_addc_u32 s1, s11, 0
	v_cvt_pk_bf16_f32 v162, v154, v155
	v_cvt_pk_bf16_f32 v163, v156, v157
	global_store_dwordx2 v89, v[162:163], s[0:1]
	v_readlane_b32 s10, v236, 47
	v_readlane_b32 s11, v236, 48
	v_readlane_b32 s0, v233, 25
	s_lshl_b32 s0, s0, 20
	s_add_u32 s10, s10, s0
	s_addc_u32 s11, s11, 0
	s_lshr_b32 s0, s23, 1
	s_lshl_b32 s0, s0, 9
	s_add_u32 s0, s0, s21
	s_lshl_b32 s0, s0, 10
	s_add_u32 s0, s0, s20
	s_lshl_b32 s0, s0, 2
	s_add_u32 s10, s10, s0
	s_addc_u32 s11, s11, 0
	s_add_u32 s0, s10, 0x0
	s_addc_u32 s1, s11, 0
	global_store_dword v195, v94, s[0:1]
	s_add_u32 s0, s10, 0x1000
	s_addc_u32 s1, s11, 0
	global_store_dword v195, v95, s[0:1]
	s_add_u32 s0, s10, 0x2000
	s_addc_u32 s1, s11, 0
	global_store_dword v195, v96, s[0:1]
	s_add_u32 s0, s10, 0x3000
	s_addc_u32 s1, s11, 0
	global_store_dword v195, v97, s[0:1]
	s_add_u32 s0, s10, 0x10
	s_addc_u32 s1, s11, 0
	global_store_dword v195, v98, s[0:1]
	s_add_u32 s0, s10, 0x1010
	s_addc_u32 s1, s11, 0
	global_store_dword v195, v99, s[0:1]
	s_add_u32 s0, s10, 0x2010
	s_addc_u32 s1, s11, 0
	global_store_dword v195, v100, s[0:1]
	s_add_u32 s0, s10, 0x3010
	s_addc_u32 s1, s11, 0
	global_store_dword v195, v101, s[0:1]
	s_add_u32 s0, s10, 0x80
	s_addc_u32 s1, s11, 0
	global_store_dword v195, v102, s[0:1]
	s_add_u32 s0, s10, 0x1080
	s_addc_u32 s1, s11, 0
	global_store_dword v195, v103, s[0:1]
	s_add_u32 s0, s10, 0x2080
	s_addc_u32 s1, s11, 0
	global_store_dword v195, v104, s[0:1]
	s_add_u32 s0, s10, 0x3080
	s_addc_u32 s1, s11, 0
	global_store_dword v195, v105, s[0:1]
	s_add_u32 s0, s10, 0x90
	s_addc_u32 s1, s11, 0
	global_store_dword v195, v106, s[0:1]
	s_add_u32 s0, s10, 0x1090
	s_addc_u32 s1, s11, 0
	global_store_dword v195, v107, s[0:1]
	s_add_u32 s0, s10, 0x2090
	s_addc_u32 s1, s11, 0
	global_store_dword v195, v108, s[0:1]
	s_add_u32 s0, s10, 0x3090
	s_addc_u32 s1, s11, 0
	global_store_dword v195, v109, s[0:1]
	s_add_u32 s0, s10, 0x10000
	s_addc_u32 s1, s11, 0
	global_store_dword v195, v110, s[0:1]
	s_add_u32 s0, s10, 0x11000
	s_addc_u32 s1, s11, 0
	global_store_dword v195, v111, s[0:1]
	s_add_u32 s0, s10, 0x12000
	s_addc_u32 s1, s11, 0
	global_store_dword v195, v112, s[0:1]
	s_add_u32 s0, s10, 0x13000
	s_addc_u32 s1, s11, 0
	global_store_dword v195, v113, s[0:1]
	s_add_u32 s0, s10, 0x10010
	s_addc_u32 s1, s11, 0
	global_store_dword v195, v114, s[0:1]
	s_add_u32 s0, s10, 0x11010
	s_addc_u32 s1, s11, 0
	global_store_dword v195, v115, s[0:1]
	s_add_u32 s0, s10, 0x12010
	s_addc_u32 s1, s11, 0
	global_store_dword v195, v116, s[0:1]
	s_add_u32 s0, s10, 0x13010
	s_addc_u32 s1, s11, 0
	global_store_dword v195, v117, s[0:1]
	s_add_u32 s0, s10, 0x10080
	s_addc_u32 s1, s11, 0
	global_store_dword v195, v118, s[0:1]
	s_add_u32 s0, s10, 0x11080
	s_addc_u32 s1, s11, 0
	global_store_dword v195, v119, s[0:1]
	s_add_u32 s0, s10, 0x12080
	s_addc_u32 s1, s11, 0
	global_store_dword v195, v120, s[0:1]
	s_add_u32 s0, s10, 0x13080
	s_addc_u32 s1, s11, 0
	global_store_dword v195, v121, s[0:1]
	s_add_u32 s0, s10, 0x10090
	s_addc_u32 s1, s11, 0
	global_store_dword v195, v122, s[0:1]
	s_add_u32 s0, s10, 0x11090
	s_addc_u32 s1, s11, 0
	global_store_dword v195, v123, s[0:1]
	s_add_u32 s0, s10, 0x12090
	s_addc_u32 s1, s11, 0
	global_store_dword v195, v124, s[0:1]
	s_add_u32 s0, s10, 0x13090
	s_addc_u32 s1, s11, 0
	global_store_dword v195, v125, s[0:1]
	s_add_u32 s0, s10, 0x20000
	s_addc_u32 s1, s11, 0
	global_store_dword v195, v126, s[0:1]
	s_add_u32 s0, s10, 0x21000
	s_addc_u32 s1, s11, 0
	global_store_dword v195, v127, s[0:1]
	s_add_u32 s0, s10, 0x22000
	s_addc_u32 s1, s11, 0
	global_store_dword v195, v128, s[0:1]
	s_add_u32 s0, s10, 0x23000
	s_addc_u32 s1, s11, 0
	global_store_dword v195, v129, s[0:1]
	s_add_u32 s0, s10, 0x20010
	s_addc_u32 s1, s11, 0
	global_store_dword v195, v130, s[0:1]
	s_add_u32 s0, s10, 0x21010
	s_addc_u32 s1, s11, 0
	global_store_dword v195, v131, s[0:1]
	s_add_u32 s0, s10, 0x22010
	s_addc_u32 s1, s11, 0
	global_store_dword v195, v132, s[0:1]
	s_add_u32 s0, s10, 0x23010
	s_addc_u32 s1, s11, 0
	global_store_dword v195, v133, s[0:1]
	s_add_u32 s0, s10, 0x20080
	s_addc_u32 s1, s11, 0
	global_store_dword v195, v134, s[0:1]
	s_add_u32 s0, s10, 0x21080
	s_addc_u32 s1, s11, 0
	global_store_dword v195, v135, s[0:1]
	s_add_u32 s0, s10, 0x22080
	s_addc_u32 s1, s11, 0
	global_store_dword v195, v136, s[0:1]
	s_add_u32 s0, s10, 0x23080
	s_addc_u32 s1, s11, 0
	global_store_dword v195, v137, s[0:1]
	s_add_u32 s0, s10, 0x20090
	s_addc_u32 s1, s11, 0
	global_store_dword v195, v138, s[0:1]
	s_add_u32 s0, s10, 0x21090
	s_addc_u32 s1, s11, 0
	global_store_dword v195, v139, s[0:1]
	s_add_u32 s0, s10, 0x22090
	s_addc_u32 s1, s11, 0
	global_store_dword v195, v140, s[0:1]
	s_add_u32 s0, s10, 0x23090
	s_addc_u32 s1, s11, 0
	global_store_dword v195, v141, s[0:1]
	s_add_u32 s0, s10, 0x30000
	s_addc_u32 s1, s11, 0
	global_store_dword v195, v142, s[0:1]
	s_add_u32 s0, s10, 0x31000
	s_addc_u32 s1, s11, 0
	global_store_dword v195, v143, s[0:1]
	s_add_u32 s0, s10, 0x32000
	s_addc_u32 s1, s11, 0
	global_store_dword v195, v144, s[0:1]
	s_add_u32 s0, s10, 0x33000
	s_addc_u32 s1, s11, 0
	global_store_dword v195, v145, s[0:1]
	s_add_u32 s0, s10, 0x30010
	s_addc_u32 s1, s11, 0
	global_store_dword v195, v146, s[0:1]
	s_add_u32 s0, s10, 0x31010
	s_addc_u32 s1, s11, 0
	global_store_dword v195, v147, s[0:1]
	s_add_u32 s0, s10, 0x32010
	s_addc_u32 s1, s11, 0
	global_store_dword v195, v148, s[0:1]
	s_add_u32 s0, s10, 0x33010
	s_addc_u32 s1, s11, 0
	global_store_dword v195, v149, s[0:1]
	s_add_u32 s0, s10, 0x30080
	s_addc_u32 s1, s11, 0
	global_store_dword v195, v150, s[0:1]
	s_add_u32 s0, s10, 0x31080
	s_addc_u32 s1, s11, 0
	global_store_dword v195, v151, s[0:1]
	s_add_u32 s0, s10, 0x32080
	s_addc_u32 s1, s11, 0
	global_store_dword v195, v152, s[0:1]
	s_add_u32 s0, s10, 0x33080
	s_addc_u32 s1, s11, 0
	global_store_dword v195, v153, s[0:1]
	s_add_u32 s0, s10, 0x30090
	s_addc_u32 s1, s11, 0
	global_store_dword v195, v154, s[0:1]
	s_add_u32 s0, s10, 0x31090
	s_addc_u32 s1, s11, 0
	global_store_dword v195, v155, s[0:1]
	s_add_u32 s0, s10, 0x32090
	s_addc_u32 s1, s11, 0
	global_store_dword v195, v156, s[0:1]
	s_add_u32 s0, s10, 0x33090
	s_addc_u32 s1, s11, 0
	global_store_dword v195, v157, s[0:1]
	s_branch .Lv_done_b
.Lv_lat_b:
	s_sub_u32 s0, s23, 32
	s_lshr_b32 s1, s0, 5
	s_lshl_b32 s1, s1, 10
	s_add_u32 s1, s1, s20
	s_lshl_b32 s1, s1, 12
	s_and_b32 s0, s0, 31
	s_lshl_b32 s0, s0, 7
	s_add_u32 s1, s1, s0
	s_lshl_b32 s1, s1, 1
	s_add_u32 s10, s10, s1
	s_addc_u32 s11, s11, 0
	s_add_u32 s10, s10, 0x800000
	s_addc_u32 s11, s11, 0
	s_add_u32 s0, s10, 0x0
	s_addc_u32 s1, s11, 0
	v_cvt_pk_bf16_f32 v64, v94, v95
	v_cvt_pk_bf16_f32 v65, v96, v97
	global_store_dwordx2 v90, v[64:65], s[0:1]
	s_add_u32 s0, s10, 0x8000
	s_addc_u32 s1, s11, 0
	v_cvt_pk_bf16_f32 v68, v98, v99
	v_cvt_pk_bf16_f32 v69, v100, v101
	global_store_dwordx2 v90, v[68:69], s[0:1]
	s_add_u32 s0, s10, 0x40000
	s_addc_u32 s1, s11, 0
	v_cvt_pk_bf16_f32 v72, v102, v103
	v_cvt_pk_bf16_f32 v73, v104, v105
	global_store_dwordx2 v90, v[72:73], s[0:1]
	s_add_u32 s0, s10, 0x48000
	s_addc_u32 s1, s11, 0
	v_cvt_pk_bf16_f32 v76, v106, v107
	v_cvt_pk_bf16_f32 v77, v108, v109
	global_store_dwordx2 v90, v[76:77], s[0:1]
	s_add_u32 s0, s10, 0x20
	s_addc_u32 s1, s11, 0
	v_cvt_pk_bf16_f32 v80, v110, v111
	v_cvt_pk_bf16_f32 v81, v112, v113
	global_store_dwordx2 v90, v[80:81], s[0:1]
	s_add_u32 s0, s10, 0x8020
	s_addc_u32 s1, s11, 0
	v_cvt_pk_bf16_f32 v84, v114, v115
	v_cvt_pk_bf16_f32 v85, v116, v117
	global_store_dwordx2 v90, v[84:85], s[0:1]
	s_add_u32 s0, s10, 0x40020
	s_addc_u32 s1, s11, 0
	v_cvt_pk_bf16_f32 v158, v118, v119
	v_cvt_pk_bf16_f32 v159, v120, v121
	global_store_dwordx2 v90, v[158:159], s[0:1]
	s_add_u32 s0, s10, 0x48020
	s_addc_u32 s1, s11, 0
	v_cvt_pk_bf16_f32 v162, v122, v123
	v_cvt_pk_bf16_f32 v163, v124, v125
	global_store_dwordx2 v90, v[162:163], s[0:1]
	s_add_u32 s0, s10, 0x40
	s_addc_u32 s1, s11, 0
	v_cvt_pk_bf16_f32 v64, v126, v127
	v_cvt_pk_bf16_f32 v65, v128, v129
	global_store_dwordx2 v90, v[64:65], s[0:1]
	s_add_u32 s0, s10, 0x8040
	s_addc_u32 s1, s11, 0
	v_cvt_pk_bf16_f32 v68, v130, v131
	v_cvt_pk_bf16_f32 v69, v132, v133
	global_store_dwordx2 v90, v[68:69], s[0:1]
	s_add_u32 s0, s10, 0x40040
	s_addc_u32 s1, s11, 0
	v_cvt_pk_bf16_f32 v72, v134, v135
	v_cvt_pk_bf16_f32 v73, v136, v137
	global_store_dwordx2 v90, v[72:73], s[0:1]
	s_add_u32 s0, s10, 0x48040
	s_addc_u32 s1, s11, 0
	v_cvt_pk_bf16_f32 v76, v138, v139
	v_cvt_pk_bf16_f32 v77, v140, v141
	global_store_dwordx2 v90, v[76:77], s[0:1]
	s_add_u32 s0, s10, 0x60
	s_addc_u32 s1, s11, 0
	v_cvt_pk_bf16_f32 v80, v142, v143
	v_cvt_pk_bf16_f32 v81, v144, v145
	global_store_dwordx2 v90, v[80:81], s[0:1]
	s_add_u32 s0, s10, 0x8060
	s_addc_u32 s1, s11, 0
	v_cvt_pk_bf16_f32 v84, v146, v147
	v_cvt_pk_bf16_f32 v85, v148, v149
	global_store_dwordx2 v90, v[84:85], s[0:1]
	s_add_u32 s0, s10, 0x40060
	s_addc_u32 s1, s11, 0
	v_cvt_pk_bf16_f32 v158, v150, v151
	v_cvt_pk_bf16_f32 v159, v152, v153
	global_store_dwordx2 v90, v[158:159], s[0:1]
	s_add_u32 s0, s10, 0x48060
	s_addc_u32 s1, s11, 0
	v_cvt_pk_bf16_f32 v162, v154, v155
	v_cvt_pk_bf16_f32 v163, v156, v157
	global_store_dwordx2 v90, v[162:163], s[0:1]
.Lv_done_b:
.Lgie_next:
	s_add_u32 s23, s23, 16
	s_add_i32 s16, s16, -1
	s_cmp_eq_u32 s16, 0
	s_cbranch_scc1 .Lgie_exit
	s_cmp_eq_u32 s16, 1
	s_cbranch_scc0 .Lgie_iter
	s_cmpk_lt_u32 s2, 0x120
	s_cbranch_scc0 .Lgie_iter
	s_mov_b32 s23, s2
	s_movk_i32 s18, 64
	s_movk_i32 s19, 65
	s_cmp_eq_u32 s24, 2
	s_mov_b32 s24, 0
	s_cbranch_scc0 .Lgie_iter
	v_lshrrev_b32_e32 v232, 7, v228
	v_bfe_u32 v195, v93, 4, 2
	v_lshrrev_b32_e32 v90, 6, v93
	v_and_b32_e32 v90, 1, v90
	v_lshlrev_b32_e32 v90, 6, v90
	v_lshl_add_u32 v195, v195, 3, v90
	v_mul_u32_u24_e32 v89, 0x4200, v232
	v_lshl_add_u32 v89, v195, 1, v89
	v_lshlrev_b32_e32 v90, 12, v232
	v_lshl_add_u32 v90, v195, 2, v90
	s_branch .Lgie_iter
